# EpiRms epilogues (out-proj, FFN-down): batched x loads 16 in flight, g vectors loaded once, stores interleaved; same math
# speedup vs baseline: 1.0237x; 1.0237x over previous
; #define LAS __attribute__((address_space(3)))
;     __device__ __forceinline__ void fused(f32x4 (&acc)[2][2][4][2], const Unit& u, int wr, int wc, int fr, int fq, LAS unsigned char* lds, int wid, int lane) const {
;         const LAS float* S = (const LAS float*)(lds + 4096);
;         const int col0 = u.pn * BM + wc * 32 + 4 * fq;
;         stats(acc, u, wr, wc, fr, fq, lds, wid, lane, e1);
;         const bool defer = lin_in && !lin_out;
; #pragma unroll
;         for (int ai = 0; ai < 2; ++ai)
; #pragma unroll
;             for (int m = 0; m < 4; ++m) { const int r = ai * HALF + wr * 64 + m * 16 + fr; const float rs = S[r]; const int rb = ai * 8 + wr * 4 + m;
; #pragma unroll
;                 for (int bj = 0; bj < 2; ++bj)
; #pragma unroll
;                     for (int n = 0; n < 2; ++n) { const size_t orm = (size_t)(u.pm * BM + r) * D + col0 + bj * HALF + n * 16, oln = (size_t)(u.pm * BM + rb * 16 + 8 * bj + 2 * wc + n) * D + u.pn * BM + lane * 4;
;                         const f32x4 xv = *(const f32x4*)(xin + (lin_in ? oln : orm)); const f32x4 gv = *(const f32x4*)(g1 + col0 + bj * HALF + n * 16);
;                         const f32x4 o = xv + acc[ai][bj][m][n] * rs * gv; acc[ai][bj][m][n] = o; if (!defer) *(f32x4*)(x + (lin_out ? oln : orm)) = o; }
;                 asm volatile("" : "+v"(acc[ai][0][m][0]), "+v"(acc[ai][0][m][1]), "+v"(acc[ai][1][m][0]), "+v"(acc[ai][1][m][1]));
;                 asm volatile("" ::: "memory"); }
.LBB0_256:
	s_or_b64 exec, exec, s[30:31]
	v_readlane_b32 s39, v255, 14
	s_lshl_b32 s2, s20, 8
	s_add_i32 s16, s39, 5
	s_cmp_lt_u32 s16, 13
	s_cselect_b64 vcc, -1, 0
	s_and_b64 s[16:17], vcc, exec
	v_readlane_b32 s16, v255, 22
	s_cselect_b32 s35, s42, s27
	s_cselect_b32 s34, s41, s26
	v_readlane_b32 s17, v255, 23
	s_lshl_b32 s16, s16, 10
	s_ashr_i32 s17, s16, 31
	s_lshl_b64 s[30:31], s[16:17], 2
	s_add_u32 s70, s69, s30
	v_lshrrev_b32_e32 v132, 2, v156
	s_addc_u32 s71, s79, s31
	s_lshl_b32 s16, s95, 1
	v_and_b32_e32 v132, 12, v132
	s_or_b32 s16, s0, s16
	v_lshl_or_b32 v132, s95, 5, v132
	v_add_u32_e32 v148, s0, v157
	s_add_i32 s36, s16, s94
	v_or_b32_e32 v146, s2, v132
	s_ashr_i32 s17, s2, 31
	v_ashrrev_i32_e32 v149, 31, v148
	s_ashr_i32 s37, s36, 31
	v_ashrrev_i32_e32 v147, 31, v146
	v_lshl_or_b32 v154, v3, 2, s2
	v_mov_b32_e32 v155, s17
	v_lshlrev_b64 v[132:133], 10, v[148:149]
	s_lshl_b64 s[16:17], s[36:37], 10
	v_lshl_add_u32 v3, v157, 2, 0
	v_lshl_add_u64 v[152:153], v[132:133], 0, v[146:147]
	v_lshl_add_u64 v[156:157], s[16:17], 0, v[154:155]
	v_cndmask_b32_e32 v133, v157, v153, vcc
	v_cndmask_b32_e32 v132, v156, v152, vcc
	s_waitcnt lgkmcnt(0)
	s_barrier
	s_mov_b32 s94, s39
	v_lshrrev_b32_e32 v176, 8, v202
	v_bfe_u32 v177, v202, 6, 2
	v_and_b32_e32 v178, 15, v207
	v_lshrrev_b32_e32 v179, 4, v207
	s_lshl_b32 s16, s20, 10
	v_lshlrev_b32_e32 v180, 18, v176
	v_lshl_add_u32 v180, v177, 13, v180
	v_lshl_add_u32 v180, v207, 4, v180
	v_add_u32_e32 v180, s16, v180
	v_lshlrev_b32_e32 v181, 18, v176
	v_lshl_add_u32 v181, v178, 12, v181
	v_lshl_add_u32 v181, v177, 7, v181
	v_lshl_add_u32 v181, v179, 4, v181
	v_add_u32_e32 v181, s16, v181
	v_lshlrev_b32_e32 v175, 7, v177
	v_lshl_add_u32 v175, v179, 4, v175
	v_add_u32_e32 v175, s16, v175
	v_mov_b32_e32 v158, v180
	v_mov_b32_e32 v247, v181
	v_add_u32_e32 v159, 0x1000, v180
	v_add_u32_e32 v249, 0x40, v181
	v_add_u32_e32 v200, 0x8000, v180
	v_add_u32_e32 v251, 0x200, v181
	v_add_u32_e32 v201, 0x9000, v180
	v_add_u32_e32 v253, 0x240, v181
	v_cndmask_b32_e32 v247, v158, v247, vcc
	v_cndmask_b32_e32 v249, v159, v249, vcc
	v_cndmask_b32_e32 v251, v200, v251, vcc
	v_cndmask_b32_e32 v253, v201, v253, vcc
	s_lshl_b32 s16, s18, 20
	s_add_u32 s98, s34, s16
	s_addc_u32 s99, s35, 0
	s_add_u32 s100, s26, s16
	s_addc_u32 s101, s27, 0
	global_load_dwordx4 v[132:135], v175, s[70:71] offset:0
	global_load_dwordx4 v[140:143], v175, s[70:71] offset:64
	global_load_dwordx4 v[146:149], v175, s[70:71] offset:512
	global_load_dwordx4 v[150:153], v175, s[70:71] offset:576
	global_load_dwordx4 v[176:179], v247, s[98:99]
	global_load_dwordx4 v[180:183], v249, s[98:99]
	global_load_dwordx4 v[184:187], v251, s[98:99]
	global_load_dwordx4 v[188:191], v253, s[98:99]
	s_add_u32 s98, s98, 0x10000
	s_addc_u32 s99, s99, 0
	global_load_dwordx4 v[192:195], v247, s[98:99]
	global_load_dwordx4 v[196:199], v249, s[98:99]
	global_load_dwordx4 v[214:217], v251, s[98:99]
	global_load_dwordx4 v[218:221], v253, s[98:99]
	s_add_u32 s98, s98, 0x10000
	s_addc_u32 s99, s99, 0
	global_load_dwordx4 v[222:225], v247, s[98:99]
	global_load_dwordx4 v[226:229], v249, s[98:99]
	global_load_dwordx4 v[230:233], v251, s[98:99]
	global_load_dwordx4 v[234:237], v253, s[98:99]
	s_add_u32 s98, s98, 0x10000
	s_addc_u32 s99, s99, 0
	global_load_dwordx4 v[160:163], v247, s[98:99]
	global_load_dwordx4 v[164:167], v249, s[98:99]
	global_load_dwordx4 v[168:171], v251, s[98:99]
	global_load_dwordx4 v[154:157], v253, s[98:99]
	ds_read_b32 v246, v3 offset:4096
	ds_read_b32 v248, v3 offset:4160
	ds_read_b32 v250, v3 offset:4224
	ds_read_b32 v252, v3 offset:4288
	s_waitcnt lgkmcnt(3)
	v_pk_mul_f32 v[64:65], v[64:65], v[246:247] op_sel_hi:[1,0]
	v_pk_mul_f32 v[66:67], v[66:67], v[246:247] op_sel_hi:[1,0]
	v_pk_mul_f32 v[72:73], v[72:73], v[246:247] op_sel_hi:[1,0]
	v_pk_mul_f32 v[74:75], v[74:75], v[246:247] op_sel_hi:[1,0]
	v_pk_mul_f32 v[76:77], v[76:77], v[246:247] op_sel_hi:[1,0]
	v_pk_mul_f32 v[78:79], v[78:79], v[246:247] op_sel_hi:[1,0]
	v_pk_mul_f32 v[84:85], v[84:85], v[246:247] op_sel_hi:[1,0]
	v_pk_mul_f32 v[86:87], v[86:87], v[246:247] op_sel_hi:[1,0]
	s_waitcnt lgkmcnt(2)
	v_pk_mul_f32 v[92:93], v[92:93], v[248:249] op_sel_hi:[1,0]
	v_pk_mul_f32 v[94:95], v[94:95], v[248:249] op_sel_hi:[1,0]
	v_pk_mul_f32 v[96:97], v[96:97], v[248:249] op_sel_hi:[1,0]
	v_pk_mul_f32 v[98:99], v[98:99], v[248:249] op_sel_hi:[1,0]
	v_pk_mul_f32 v[104:105], v[104:105], v[248:249] op_sel_hi:[1,0]
	v_pk_mul_f32 v[106:107], v[106:107], v[248:249] op_sel_hi:[1,0]
	v_pk_mul_f32 v[108:109], v[108:109], v[248:249] op_sel_hi:[1,0]
	v_pk_mul_f32 v[110:111], v[110:111], v[248:249] op_sel_hi:[1,0]
	s_waitcnt lgkmcnt(1)
	v_pk_mul_f32 v[116:117], v[116:117], v[250:251] op_sel_hi:[1,0]
	v_pk_mul_f32 v[118:119], v[118:119], v[250:251] op_sel_hi:[1,0]
	v_pk_mul_f32 v[124:125], v[124:125], v[250:251] op_sel_hi:[1,0]
	v_pk_mul_f32 v[126:127], v[126:127], v[250:251] op_sel_hi:[1,0]
	v_pk_mul_f32 v[128:129], v[128:129], v[250:251] op_sel_hi:[1,0]
	v_pk_mul_f32 v[130:131], v[130:131], v[250:251] op_sel_hi:[1,0]
	v_pk_mul_f32 v[120:121], v[120:121], v[250:251] op_sel_hi:[1,0]
	v_pk_mul_f32 v[122:123], v[122:123], v[250:251] op_sel_hi:[1,0]
	s_waitcnt lgkmcnt(0)
	v_pk_mul_f32 v[112:113], v[112:113], v[252:253] op_sel_hi:[1,0]
	v_pk_mul_f32 v[114:115], v[114:115], v[252:253] op_sel_hi:[1,0]
	v_pk_mul_f32 v[100:101], v[100:101], v[252:253] op_sel_hi:[1,0]
	v_pk_mul_f32 v[102:103], v[102:103], v[252:253] op_sel_hi:[1,0]
	v_pk_mul_f32 v[88:89], v[88:89], v[252:253] op_sel_hi:[1,0]
	v_pk_mul_f32 v[90:91], v[90:91], v[252:253] op_sel_hi:[1,0]
	v_pk_mul_f32 v[80:81], v[80:81], v[252:253] op_sel_hi:[1,0]
	v_pk_mul_f32 v[82:83], v[82:83], v[252:253] op_sel_hi:[1,0]
	ds_read_b32 v246, v3 offset:4608
	ds_read_b32 v248, v3 offset:4672
	ds_read_b32 v250, v3 offset:4736
	ds_read_b32 v252, v3 offset:4800
	s_waitcnt lgkmcnt(3)
;     __device__ __forceinline__ void fused(f32x4 (&acc)[2][2][4][2], const Unit& u, int wr, int wc, int fr, int fq, LAS unsigned char* lds, int wid, int lane) const {
;     ...
;         for (int ai = 0; ai < 2; ++ai)
; #pragma unroll
;             for (int m = 0; m < 4; ++m) { const int r = ai * HALF + wr * 64 + m * 16 + fr; const float rs = S[r]; const int rb = ai * 8 + wr * 4 + m;
; #pragma unroll
;                 for (int bj = 0; bj < 2; ++bj)
; #pragma unroll
;                     for (int n = 0; n < 2; ++n) { const size_t orm = (size_t)(u.pm * BM + r) * D + col0 + bj * HALF + n * 16, oln = (size_t)(u.pm * BM + rb * 16 + 8 * bj + 2 * wc + n) * D + u.pn * BM + lane * 4;
;                         const f32x4 xv = *(const f32x4*)(xin + (lin_in ? oln : orm)); const f32x4 gv = *(const f32x4*)(g1 + col0 + bj * HALF + n * 16);
;                         const f32x4 o = xv + acc[ai][bj][m][n] * rs * gv; acc[ai][bj][m][n] = o; if (!defer) *(f32x4*)(x + (lin_out ? oln : orm)) = o; }
;                 asm volatile("" : "+v"(acc[ai][0][m][0]), "+v"(acc[ai][0][m][1]), "+v"(acc[ai][1][m][0]), "+v"(acc[ai][1][m][1]));
;                 asm volatile("" ::: "memory"); }
	v_pk_mul_f32 v[68:69], v[68:69], v[246:247] op_sel_hi:[1,0]
	v_pk_mul_f32 v[70:71], v[70:71], v[246:247] op_sel_hi:[1,0]
	v_pk_mul_f32 v[60:61], v[60:61], v[246:247] op_sel_hi:[1,0]
	v_pk_mul_f32 v[62:63], v[62:63], v[246:247] op_sel_hi:[1,0]
	v_pk_mul_f32 v[56:57], v[56:57], v[246:247] op_sel_hi:[1,0]
	v_pk_mul_f32 v[58:59], v[58:59], v[246:247] op_sel_hi:[1,0]
	v_pk_mul_f32 v[52:53], v[52:53], v[246:247] op_sel_hi:[1,0]
	v_pk_mul_f32 v[54:55], v[54:55], v[246:247] op_sel_hi:[1,0]
	s_waitcnt lgkmcnt(2)
	v_pk_mul_f32 v[48:49], v[48:49], v[248:249] op_sel_hi:[1,0]
	v_pk_mul_f32 v[50:51], v[50:51], v[248:249] op_sel_hi:[1,0]
	v_pk_mul_f32 v[44:45], v[44:45], v[248:249] op_sel_hi:[1,0]
	v_pk_mul_f32 v[46:47], v[46:47], v[248:249] op_sel_hi:[1,0]
	v_pk_mul_f32 v[40:41], v[40:41], v[248:249] op_sel_hi:[1,0]
	v_pk_mul_f32 v[42:43], v[42:43], v[248:249] op_sel_hi:[1,0]
	v_pk_mul_f32 v[36:37], v[36:37], v[248:249] op_sel_hi:[1,0]
	v_pk_mul_f32 v[38:39], v[38:39], v[248:249] op_sel_hi:[1,0]
	s_waitcnt lgkmcnt(1)
	v_pk_mul_f32 v[32:33], v[32:33], v[250:251] op_sel_hi:[1,0]
	v_pk_mul_f32 v[34:35], v[34:35], v[250:251] op_sel_hi:[1,0]
	v_pk_mul_f32 v[28:29], v[28:29], v[250:251] op_sel_hi:[1,0]
	v_pk_mul_f32 v[30:31], v[30:31], v[250:251] op_sel_hi:[1,0]
	v_pk_mul_f32 v[24:25], v[24:25], v[250:251] op_sel_hi:[1,0]
	v_pk_mul_f32 v[26:27], v[26:27], v[250:251] op_sel_hi:[1,0]
	v_pk_mul_f32 v[20:21], v[20:21], v[250:251] op_sel_hi:[1,0]
	v_pk_mul_f32 v[22:23], v[22:23], v[250:251] op_sel_hi:[1,0]
	s_waitcnt lgkmcnt(0)
	v_pk_mul_f32 v[16:17], v[16:17], v[252:253] op_sel_hi:[1,0]
	v_pk_mul_f32 v[18:19], v[18:19], v[252:253] op_sel_hi:[1,0]
	v_pk_mul_f32 v[12:13], v[12:13], v[252:253] op_sel_hi:[1,0]
	v_pk_mul_f32 v[14:15], v[14:15], v[252:253] op_sel_hi:[1,0]
	v_pk_mul_f32 v[8:9], v[8:9], v[252:253] op_sel_hi:[1,0]
	v_pk_mul_f32 v[10:11], v[10:11], v[252:253] op_sel_hi:[1,0]
	v_pk_mul_f32 v[4:5], v[4:5], v[252:253] op_sel_hi:[1,0]
	v_pk_mul_f32 v[6:7], v[6:7], v[252:253] op_sel_hi:[1,0]
	s_waitcnt vmcnt(15)
	v_pk_fma_f32 v[64:65], v[132:133], v[64:65], v[176:177]
	v_pk_fma_f32 v[66:67], v[134:135], v[66:67], v[178:179]
	global_store_dwordx4 v158, v[64:67], s[100:101]
	s_add_u32 s98, s98, 0x50000
	s_addc_u32 s99, s99, 0
	global_load_dwordx4 v[176:179], v247, s[98:99]
	s_waitcnt vmcnt(16)
	v_pk_fma_f32 v[72:73], v[140:141], v[72:73], v[180:181]
	v_pk_fma_f32 v[74:75], v[142:143], v[74:75], v[182:183]
	global_store_dwordx4 v159, v[72:75], s[100:101]
	global_load_dwordx4 v[180:183], v249, s[98:99]
	s_waitcnt vmcnt(17)
	v_pk_fma_f32 v[76:77], v[146:147], v[76:77], v[184:185]
	v_pk_fma_f32 v[78:79], v[148:149], v[78:79], v[186:187]
	global_store_dwordx4 v200, v[76:79], s[100:101]
	global_load_dwordx4 v[184:187], v251, s[98:99]
	s_waitcnt vmcnt(18)
	v_pk_fma_f32 v[84:85], v[150:151], v[84:85], v[188:189]
	v_pk_fma_f32 v[86:87], v[152:153], v[86:87], v[190:191]
	global_store_dwordx4 v201, v[84:87], s[100:101]
	global_load_dwordx4 v[188:191], v253, s[98:99]
	s_waitcnt vmcnt(19)
	v_pk_fma_f32 v[92:93], v[132:133], v[92:93], v[192:193]
	v_pk_fma_f32 v[94:95], v[134:135], v[94:95], v[194:195]
	s_add_u32 s100, s100, 0x10000
	s_addc_u32 s101, s101, 0
	global_store_dwordx4 v158, v[92:95], s[100:101]
	s_add_u32 s98, s98, 0x10000
	s_addc_u32 s99, s99, 0
	global_load_dwordx4 v[192:195], v247, s[98:99]
	s_waitcnt vmcnt(20)
	v_pk_fma_f32 v[96:97], v[140:141], v[96:97], v[196:197]
	v_pk_fma_f32 v[98:99], v[142:143], v[98:99], v[198:199]
	global_store_dwordx4 v159, v[96:99], s[100:101]
	global_load_dwordx4 v[196:199], v249, s[98:99]
	s_waitcnt vmcnt(21)
	v_pk_fma_f32 v[104:105], v[146:147], v[104:105], v[214:215]
	v_pk_fma_f32 v[106:107], v[148:149], v[106:107], v[216:217]
	global_store_dwordx4 v200, v[104:107], s[100:101]
	global_load_dwordx4 v[214:217], v251, s[98:99]
	s_waitcnt vmcnt(22)
	v_pk_fma_f32 v[108:109], v[150:151], v[108:109], v[218:219]
	v_pk_fma_f32 v[110:111], v[152:153], v[110:111], v[220:221]
	global_store_dwordx4 v201, v[108:111], s[100:101]
	global_load_dwordx4 v[218:221], v253, s[98:99]
	s_waitcnt vmcnt(23)
	v_pk_fma_f32 v[116:117], v[132:133], v[116:117], v[222:223]
	v_pk_fma_f32 v[118:119], v[134:135], v[118:119], v[224:225]
	s_add_u32 s100, s100, 0x10000
	s_addc_u32 s101, s101, 0
	global_store_dwordx4 v158, v[116:119], s[100:101]
	s_add_u32 s98, s98, 0x10000
	s_addc_u32 s99, s99, 0
	global_load_dwordx4 v[222:225], v247, s[98:99]
	s_waitcnt vmcnt(24)
	v_pk_fma_f32 v[124:125], v[140:141], v[124:125], v[226:227]
	v_pk_fma_f32 v[126:127], v[142:143], v[126:127], v[228:229]
	global_store_dwordx4 v159, v[124:127], s[100:101]
	global_load_dwordx4 v[226:229], v249, s[98:99]
	s_waitcnt vmcnt(25)
	v_pk_fma_f32 v[128:129], v[146:147], v[128:129], v[230:231]
	v_pk_fma_f32 v[130:131], v[148:149], v[130:131], v[232:233]
	global_store_dwordx4 v200, v[128:131], s[100:101]
	global_load_dwordx4 v[230:233], v251, s[98:99]
	s_waitcnt vmcnt(26)
	v_pk_fma_f32 v[120:121], v[150:151], v[120:121], v[234:235]
	v_pk_fma_f32 v[122:123], v[152:153], v[122:123], v[236:237]
	global_store_dwordx4 v201, v[120:123], s[100:101]
	global_load_dwordx4 v[234:237], v253, s[98:99]
	s_waitcnt vmcnt(27)
; #define LAS __attribute__((address_space(3)))
;     __device__ __forceinline__ void stats(const f32x4 (&v)[2][2][4][2], const Unit& u, int wr, int wc, int fr, int fq, LAS unsigned char* lds, int wid, int lane, const RmsX& e) const {
;         LAS float* P = (LAS float*)lds; LAS float* S = (LAS float*)(lds + 4096);
; #pragma unroll
;         for (int ai = 0; ai < 2; ++ai)
; #pragma unroll
;             for (int m = 0; m < 4; ++m) { float s = 0.f;
; #pragma unroll
;                 for (int bj = 0; bj < 2; ++bj)
; #pragma unroll
;                     for (int n = 0; n < 2; ++n) { const f32x4 t = v[ai][bj][m][n]; s += (t[0] * t[0] + t[1] * t[1]) + (t[2] * t[2] + t[3] * t[3]); }
;                 s += __shfl_xor(s, 16); s += __shfl_xor(s, 32);
;                 if (fq == 0) P[(ai * HALF + wr * 64 + m * 16 + fr) * 4 + wc] = s; }
;     __device__ __forceinline__ void fused(f32x4 (&acc)[2][2][4][2], const Unit& u, int wr, int wc, int fr, int fq, LAS unsigned char* lds, int wid, int lane) const {
;     ...
;         for (int ai = 0; ai < 2; ++ai)
; #pragma unroll
;             for (int m = 0; m < 4; ++m) { const int r = ai * HALF + wr * 64 + m * 16 + fr; const float rs = S[r]; const int rb = ai * 8 + wr * 4 + m;
; #pragma unroll
;                 for (int bj = 0; bj < 2; ++bj)
; #pragma unroll
;                     for (int n = 0; n < 2; ++n) { const size_t orm = (size_t)(u.pm * BM + r) * D + col0 + bj * HALF + n * 16, oln = (size_t)(u.pm * BM + rb * 16 + 8 * bj + 2 * wc + n) * D + u.pn * BM + lane * 4;
;                         const f32x4 xv = *(const f32x4*)(xin + (lin_in ? oln : orm)); const f32x4 gv = *(const f32x4*)(g1 + col0 + bj * HALF + n * 16);
;                         const f32x4 o = xv + acc[ai][bj][m][n] * rs * gv; acc[ai][bj][m][n] = o; if (!defer) *(f32x4*)(x + (lin_out ? oln : orm)) = o; }
;                 asm volatile("" : "+v"(acc[ai][0][m][0]), "+v"(acc[ai][0][m][1]), "+v"(acc[ai][1][m][0]), "+v"(acc[ai][1][m][1]));
;                 asm volatile("" ::: "memory"); }
	v_pk_fma_f32 v[112:113], v[132:133], v[112:113], v[160:161]
	v_pk_fma_f32 v[114:115], v[134:135], v[114:115], v[162:163]
	s_add_u32 s100, s100, 0x10000
	s_addc_u32 s101, s101, 0
	global_store_dwordx4 v158, v[112:115], s[100:101]
	s_add_u32 s98, s98, 0x10000
	s_addc_u32 s99, s99, 0
	global_load_dwordx4 v[160:163], v247, s[98:99]
	s_waitcnt vmcnt(28)
	v_pk_fma_f32 v[100:101], v[140:141], v[100:101], v[164:165]
	v_pk_fma_f32 v[102:103], v[142:143], v[102:103], v[166:167]
	global_store_dwordx4 v159, v[100:103], s[100:101]
	global_load_dwordx4 v[164:167], v249, s[98:99]
	s_waitcnt vmcnt(29)
	v_pk_fma_f32 v[88:89], v[146:147], v[88:89], v[168:169]
	v_pk_fma_f32 v[90:91], v[148:149], v[90:91], v[170:171]
	global_store_dwordx4 v200, v[88:91], s[100:101]
	global_load_dwordx4 v[168:171], v251, s[98:99]
	s_waitcnt vmcnt(30)
	v_pk_fma_f32 v[80:81], v[150:151], v[80:81], v[154:155]
	v_pk_fma_f32 v[82:83], v[152:153], v[82:83], v[156:157]
	global_store_dwordx4 v201, v[80:83], s[100:101]
	global_load_dwordx4 v[154:157], v253, s[98:99]
	s_waitcnt vmcnt(30)
	v_pk_fma_f32 v[68:69], v[132:133], v[68:69], v[176:177]
	v_pk_fma_f32 v[70:71], v[134:135], v[70:71], v[178:179]
	s_add_u32 s100, s100, 0x50000
	s_addc_u32 s101, s101, 0
	global_store_dwordx4 v158, v[68:71], s[100:101]
	s_waitcnt vmcnt(29)
	v_pk_fma_f32 v[60:61], v[140:141], v[60:61], v[180:181]
	v_pk_fma_f32 v[62:63], v[142:143], v[62:63], v[182:183]
	global_store_dwordx4 v159, v[60:63], s[100:101]
	s_waitcnt vmcnt(28)
	v_pk_fma_f32 v[56:57], v[146:147], v[56:57], v[184:185]
	v_pk_fma_f32 v[58:59], v[148:149], v[58:59], v[186:187]
	global_store_dwordx4 v200, v[56:59], s[100:101]
	s_waitcnt vmcnt(27)
	v_pk_fma_f32 v[52:53], v[150:151], v[52:53], v[188:189]
	v_pk_fma_f32 v[54:55], v[152:153], v[54:55], v[190:191]
	global_store_dwordx4 v201, v[52:55], s[100:101]
	s_waitcnt vmcnt(26)
	v_pk_fma_f32 v[48:49], v[132:133], v[48:49], v[192:193]
	v_pk_fma_f32 v[50:51], v[134:135], v[50:51], v[194:195]
	s_add_u32 s100, s100, 0x10000
	s_addc_u32 s101, s101, 0
	global_store_dwordx4 v158, v[48:51], s[100:101]
	s_waitcnt vmcnt(25)
	v_pk_fma_f32 v[44:45], v[140:141], v[44:45], v[196:197]
	v_pk_fma_f32 v[46:47], v[142:143], v[46:47], v[198:199]
	global_store_dwordx4 v159, v[44:47], s[100:101]
	s_waitcnt vmcnt(24)
	v_pk_fma_f32 v[40:41], v[146:147], v[40:41], v[214:215]
	v_pk_fma_f32 v[42:43], v[148:149], v[42:43], v[216:217]
	global_store_dwordx4 v200, v[40:43], s[100:101]
	s_waitcnt vmcnt(23)
	v_pk_fma_f32 v[36:37], v[150:151], v[36:37], v[218:219]
	v_pk_fma_f32 v[38:39], v[152:153], v[38:39], v[220:221]
	global_store_dwordx4 v201, v[36:39], s[100:101]
	s_waitcnt vmcnt(22)
	v_pk_fma_f32 v[32:33], v[132:133], v[32:33], v[222:223]
	v_pk_fma_f32 v[34:35], v[134:135], v[34:35], v[224:225]
	s_add_u32 s100, s100, 0x10000
	s_addc_u32 s101, s101, 0
	global_store_dwordx4 v158, v[32:35], s[100:101]
	s_waitcnt vmcnt(21)
	v_pk_fma_f32 v[28:29], v[140:141], v[28:29], v[226:227]
	v_pk_fma_f32 v[30:31], v[142:143], v[30:31], v[228:229]
	global_store_dwordx4 v159, v[28:31], s[100:101]
	s_waitcnt vmcnt(20)
	v_pk_fma_f32 v[24:25], v[146:147], v[24:25], v[230:231]
	v_pk_fma_f32 v[26:27], v[148:149], v[26:27], v[232:233]
	global_store_dwordx4 v200, v[24:27], s[100:101]
	s_waitcnt vmcnt(19)
	v_pk_fma_f32 v[20:21], v[150:151], v[20:21], v[234:235]
	v_pk_fma_f32 v[22:23], v[152:153], v[22:23], v[236:237]
	global_store_dwordx4 v201, v[20:23], s[100:101]
	s_waitcnt vmcnt(18)
	v_pk_fma_f32 v[16:17], v[132:133], v[16:17], v[160:161]
	v_pk_fma_f32 v[18:19], v[134:135], v[18:19], v[162:163]
	s_add_u32 s100, s100, 0x10000
	s_addc_u32 s101, s101, 0
	global_store_dwordx4 v158, v[16:19], s[100:101]
	s_waitcnt vmcnt(17)
	v_pk_fma_f32 v[12:13], v[140:141], v[12:13], v[164:165]
	v_pk_fma_f32 v[14:15], v[142:143], v[14:15], v[166:167]
	global_store_dwordx4 v159, v[12:15], s[100:101]
	s_waitcnt vmcnt(16)
	v_pk_fma_f32 v[8:9], v[146:147], v[8:9], v[168:169]
	v_pk_fma_f32 v[10:11], v[148:149], v[10:11], v[170:171]
	global_store_dwordx4 v200, v[8:11], s[100:101]
	s_waitcnt vmcnt(15)
	v_pk_fma_f32 v[4:5], v[150:151], v[4:5], v[154:155]
	v_pk_fma_f32 v[6:7], v[152:153], v[6:7], v[156:157]
	global_store_dwordx4 v201, v[4:7], s[100:101]
	s_cmp_eq_u64 s[12:13], 0
	s_cbranch_scc1 .LBB0_291
	v_mul_f32_e32 v132, v65, v65
	v_mul_f32_e32 v133, v67, v67
	v_fmac_f32_e32 v132, v64, v64
	v_fmac_f32_e32 v133, v66, v66
	v_add_f32_e32 v132, v132, v133
	v_mul_f32_e32 v133, v73, v73
	v_mul_f32_e32 v134, v75, v75
	v_fmac_f32_e32 v133, v72, v72
	v_fmac_f32_e32 v134, v74, v74
	v_add_f32_e32 v133, v133, v134
	v_add_f32_e32 v132, v132, v133
	v_mul_f32_e32 v133, v77, v77
	v_mul_f32_e32 v134, v79, v79
	v_fmac_f32_e32 v133, v76, v76
	v_fmac_f32_e32 v134, v78, v78
	v_add_f32_e32 v133, v133, v134
	v_add_f32_e32 v132, v133, v132
	v_mul_f32_e32 v133, v85, v85
	v_mul_f32_e32 v134, v87, v87
	v_fmac_f32_e32 v133, v84, v84
	v_fmac_f32_e32 v134, v86, v86
	v_add_f32_e32 v133, v133, v134
	v_add_f32_e32 v132, v133, v132
	ds_bpermute_b32 v133, v172, v132
	s_waitcnt lgkmcnt(0)
	v_add_f32_e32 v154, v132, v133
	ds_bpermute_b32 v155, v173, v154
	s_and_saveexec_b64 s[26:27], s[4:5]
	s_cbranch_execz .LBB0_259
	s_lshl_b32 s0, s23, 10
	s_add_i32 s0, s19, s0
	s_waitcnt lgkmcnt(0)
	v_add_f32_e32 v132, v154, v155
	v_lshl_add_u32 v133, v145, 4, s0
	ds_write_b32 v133, v132

; __device__ __forceinline__ unsigned pk2(float lo, float hi) { unsigned r; asm("v_cvt_pk_bf16_f32 %0, %1, %2" : "=v"(r) : "v"(lo), "v"(hi)); return r; }
;     __device__ __forceinline__ void fused(f32x4 (&acc)[2][2][4][2], const Unit& u, int wr, int wc, int fr, int fq, LAS unsigned char* lds, int wid, int lane) const {
;     ...
; #pragma unroll
;             for (int ai = 0; ai < 2; ++ai)
; #pragma unroll
;                 for (int m = 0; m < 4; ++m) { const int r = ai * HALF + wr * 64 + m * 16 + fr; const float rs = S[r]; bf16_t* hp = h + (size_t)(u.pm * BM + r) * D + col0;
; #pragma unroll
;                     for (int bj = 0; bj < 2; ++bj)
; #pragma unroll
;                         for (int n = 0; n < 2; ++n) { const f32x4 gv = *(const f32x4*)(g2 + col0 + bj * HALF + n * 16); const f32x4 o = acc[ai][bj][m][n] * rs * gv;
;                             u32x2 w; w.x = pk2(o[0], o[1]); w.y = pk2(o[2], o[3]); *(u32x2*)(hp + bj * HALF + n * 16) = w; }
;                     asm volatile("" ::: "memory"); }
.LBB0_290:
	s_or_b64 exec, exec, s[8:9]
	s_add_u32 s4, s22, s30
	s_addc_u32 s5, s33, s31
	s_waitcnt lgkmcnt(0)
	s_barrier
	v_lshrrev_b32_e32 v177, 8, v202
	v_bfe_u32 v178, v202, 6, 2
	v_and_b32_e32 v179, 15, v207
	v_lshrrev_b32_e32 v180, 4, v207
	s_lshl_b32 s16, s20, 10
	v_lshlrev_b32_e32 v175, 7, v178
	v_lshl_add_u32 v175, v180, 4, v175
	v_add_u32_e32 v175, s16, v175
	s_lshl_b32 s16, s20, 9
	v_lshlrev_b32_e32 v176, 17, v177
	v_lshl_add_u32 v176, v179, 11, v176
	v_lshl_add_u32 v176, v178, 6, v176
	v_lshl_add_u32 v176, v180, 3, v176
	v_add_u32_e32 v176, s16, v176
	s_lshl_b32 s16, s18, 19
	s_add_u32 s98, s12, s16
	s_addc_u32 s99, s13, 0
	global_load_dwordx4 v[132:135], v175, s[4:5] offset:0
	global_load_dwordx4 v[140:143], v175, s[4:5] offset:64
	global_load_dwordx4 v[146:149], v175, s[4:5] offset:512
	global_load_dwordx4 v[150:153], v175, s[4:5] offset:576
	ds_read_b32 v246, v3 offset:4096
	ds_read_b32 v248, v3 offset:4160
	ds_read_b32 v250, v3 offset:4224
	ds_read_b32 v252, v3 offset:4288
	s_waitcnt lgkmcnt(3)
	v_pk_mul_f32 v[64:65], v[64:65], v[246:247] op_sel_hi:[1,0]
	v_pk_mul_f32 v[66:67], v[66:67], v[246:247] op_sel_hi:[1,0]
	s_waitcnt vmcnt(0)
	v_pk_mul_f32 v[64:65], v[132:133], v[64:65]
	v_pk_mul_f32 v[66:67], v[134:135], v[66:67]
	v_cvt_pk_bf16_f32 v64, v64, v65
	v_cvt_pk_bf16_f32 v65, v66, v67
	global_store_dwordx2 v176, v[64:65], s[98:99] offset:0
	v_pk_mul_f32 v[72:73], v[72:73], v[246:247] op_sel_hi:[1,0]
	v_pk_mul_f32 v[74:75], v[74:75], v[246:247] op_sel_hi:[1,0]
	v_pk_mul_f32 v[72:73], v[140:141], v[72:73]
	v_pk_mul_f32 v[74:75], v[142:143], v[74:75]
	v_cvt_pk_bf16_f32 v72, v72, v73
	v_cvt_pk_bf16_f32 v73, v74, v75
	global_store_dwordx2 v176, v[72:73], s[98:99] offset:32
	v_pk_mul_f32 v[76:77], v[76:77], v[246:247] op_sel_hi:[1,0]
	v_pk_mul_f32 v[78:79], v[78:79], v[246:247] op_sel_hi:[1,0]
	v_pk_mul_f32 v[76:77], v[146:147], v[76:77]
	v_pk_mul_f32 v[78:79], v[148:149], v[78:79]
	v_cvt_pk_bf16_f32 v76, v76, v77
	v_cvt_pk_bf16_f32 v77, v78, v79
	global_store_dwordx2 v176, v[76:77], s[98:99] offset:256
	v_pk_mul_f32 v[84:85], v[84:85], v[246:247] op_sel_hi:[1,0]
	v_pk_mul_f32 v[86:87], v[86:87], v[246:247] op_sel_hi:[1,0]
	v_pk_mul_f32 v[84:85], v[150:151], v[84:85]
	v_pk_mul_f32 v[86:87], v[152:153], v[86:87]
	v_cvt_pk_bf16_f32 v84, v84, v85
	v_cvt_pk_bf16_f32 v85, v86, v87
	global_store_dwordx2 v176, v[84:85], s[98:99] offset:288
	s_waitcnt lgkmcnt(2)
	s_add_u32 s98, s98, 0x8000
	s_addc_u32 s99, s99, 0
	v_pk_mul_f32 v[92:93], v[92:93], v[248:249] op_sel_hi:[1,0]
	v_pk_mul_f32 v[94:95], v[94:95], v[248:249] op_sel_hi:[1,0]
	v_pk_mul_f32 v[92:93], v[132:133], v[92:93]
	v_pk_mul_f32 v[94:95], v[134:135], v[94:95]
	v_cvt_pk_bf16_f32 v92, v92, v93
	v_cvt_pk_bf16_f32 v93, v94, v95
	global_store_dwordx2 v176, v[92:93], s[98:99] offset:0
	v_pk_mul_f32 v[96:97], v[96:97], v[248:249] op_sel_hi:[1,0]
	v_pk_mul_f32 v[98:99], v[98:99], v[248:249] op_sel_hi:[1,0]
	v_pk_mul_f32 v[96:97], v[140:141], v[96:97]
	v_pk_mul_f32 v[98:99], v[142:143], v[98:99]
	v_cvt_pk_bf16_f32 v96, v96, v97
	v_cvt_pk_bf16_f32 v97, v98, v99
	global_store_dwordx2 v176, v[96:97], s[98:99] offset:32
	v_pk_mul_f32 v[104:105], v[104:105], v[248:249] op_sel_hi:[1,0]
	v_pk_mul_f32 v[106:107], v[106:107], v[248:249] op_sel_hi:[1,0]
	v_pk_mul_f32 v[104:105], v[146:147], v[104:105]
	v_pk_mul_f32 v[106:107], v[148:149], v[106:107]
	v_cvt_pk_bf16_f32 v104, v104, v105
	v_cvt_pk_bf16_f32 v105, v106, v107
	global_store_dwordx2 v176, v[104:105], s[98:99] offset:256
	v_pk_mul_f32 v[108:109], v[108:109], v[248:249] op_sel_hi:[1,0]
	v_pk_mul_f32 v[110:111], v[110:111], v[248:249] op_sel_hi:[1,0]
	v_pk_mul_f32 v[108:109], v[150:151], v[108:109]
	v_pk_mul_f32 v[110:111], v[152:153], v[110:111]
	v_cvt_pk_bf16_f32 v108, v108, v109
	v_cvt_pk_bf16_f32 v109, v110, v111
	global_store_dwordx2 v176, v[108:109], s[98:99] offset:288
	s_waitcnt lgkmcnt(1)
	s_add_u32 s98, s98, 0x8000
	s_addc_u32 s99, s99, 0
	v_pk_mul_f32 v[116:117], v[116:117], v[250:251] op_sel_hi:[1,0]
	v_pk_mul_f32 v[118:119], v[118:119], v[250:251] op_sel_hi:[1,0]
	v_pk_mul_f32 v[116:117], v[132:133], v[116:117]
	v_pk_mul_f32 v[118:119], v[134:135], v[118:119]
	v_cvt_pk_bf16_f32 v116, v116, v117
	v_cvt_pk_bf16_f32 v117, v118, v119
	global_store_dwordx2 v176, v[116:117], s[98:99] offset:0
	v_pk_mul_f32 v[124:125], v[124:125], v[250:251] op_sel_hi:[1,0]
	v_pk_mul_f32 v[126:127], v[126:127], v[250:251] op_sel_hi:[1,0]
	v_pk_mul_f32 v[124:125], v[140:141], v[124:125]
	v_pk_mul_f32 v[126:127], v[142:143], v[126:127]
	v_cvt_pk_bf16_f32 v124, v124, v125
	v_cvt_pk_bf16_f32 v125, v126, v127
	global_store_dwordx2 v176, v[124:125], s[98:99] offset:32
	v_pk_mul_f32 v[128:129], v[128:129], v[250:251] op_sel_hi:[1,0]
	v_pk_mul_f32 v[130:131], v[130:131], v[250:251] op_sel_hi:[1,0]
	v_pk_mul_f32 v[128:129], v[146:147], v[128:129]
	v_pk_mul_f32 v[130:131], v[148:149], v[130:131]
	v_cvt_pk_bf16_f32 v128, v128, v129
	v_cvt_pk_bf16_f32 v129, v130, v131
	global_store_dwordx2 v176, v[128:129], s[98:99] offset:256
	v_pk_mul_f32 v[120:121], v[120:121], v[250:251] op_sel_hi:[1,0]
	v_pk_mul_f32 v[122:123], v[122:123], v[250:251] op_sel_hi:[1,0]
	v_pk_mul_f32 v[120:121], v[150:151], v[120:121]
	v_pk_mul_f32 v[122:123], v[152:153], v[122:123]
	v_cvt_pk_bf16_f32 v120, v120, v121
	v_cvt_pk_bf16_f32 v121, v122, v123
	global_store_dwordx2 v176, v[120:121], s[98:99] offset:288
	s_waitcnt lgkmcnt(0)
; __device__ __forceinline__ unsigned pk2(float lo, float hi) { unsigned r; asm("v_cvt_pk_bf16_f32 %0, %1, %2" : "=v"(r) : "v"(lo), "v"(hi)); return r; }
;     __device__ __forceinline__ void fused(f32x4 (&acc)[2][2][4][2], const Unit& u, int wr, int wc, int fr, int fq, LAS unsigned char* lds, int wid, int lane) const {
;     ...
; #pragma unroll
;             for (int ai = 0; ai < 2; ++ai)
; #pragma unroll
;                 for (int m = 0; m < 4; ++m) { const int r = ai * HALF + wr * 64 + m * 16 + fr; const float rs = S[r]; bf16_t* hp = h + (size_t)(u.pm * BM + r) * D + col0;
; #pragma unroll
;                     for (int bj = 0; bj < 2; ++bj)
; #pragma unroll
;                         for (int n = 0; n < 2; ++n) { const f32x4 gv = *(const f32x4*)(g2 + col0 + bj * HALF + n * 16); const f32x4 o = acc[ai][bj][m][n] * rs * gv;
;                             u32x2 w; w.x = pk2(o[0], o[1]); w.y = pk2(o[2], o[3]); *(u32x2*)(hp + bj * HALF + n * 16) = w; }
;                     asm volatile("" ::: "memory"); }
	s_add_u32 s98, s98, 0x8000
	s_addc_u32 s99, s99, 0
	v_pk_mul_f32 v[112:113], v[112:113], v[252:253] op_sel_hi:[1,0]
	v_pk_mul_f32 v[114:115], v[114:115], v[252:253] op_sel_hi:[1,0]
	v_pk_mul_f32 v[112:113], v[132:133], v[112:113]
	v_pk_mul_f32 v[114:115], v[134:135], v[114:115]
	v_cvt_pk_bf16_f32 v112, v112, v113
	v_cvt_pk_bf16_f32 v113, v114, v115
	global_store_dwordx2 v176, v[112:113], s[98:99] offset:0
	v_pk_mul_f32 v[100:101], v[100:101], v[252:253] op_sel_hi:[1,0]
	v_pk_mul_f32 v[102:103], v[102:103], v[252:253] op_sel_hi:[1,0]
	v_pk_mul_f32 v[100:101], v[140:141], v[100:101]
	v_pk_mul_f32 v[102:103], v[142:143], v[102:103]
	v_cvt_pk_bf16_f32 v100, v100, v101
	v_cvt_pk_bf16_f32 v101, v102, v103
	global_store_dwordx2 v176, v[100:101], s[98:99] offset:32
	v_pk_mul_f32 v[88:89], v[88:89], v[252:253] op_sel_hi:[1,0]
	v_pk_mul_f32 v[90:91], v[90:91], v[252:253] op_sel_hi:[1,0]
	v_pk_mul_f32 v[88:89], v[146:147], v[88:89]
	v_pk_mul_f32 v[90:91], v[148:149], v[90:91]
	v_cvt_pk_bf16_f32 v88, v88, v89
	v_cvt_pk_bf16_f32 v89, v90, v91
	global_store_dwordx2 v176, v[88:89], s[98:99] offset:256
	v_pk_mul_f32 v[80:81], v[80:81], v[252:253] op_sel_hi:[1,0]
	v_pk_mul_f32 v[82:83], v[82:83], v[252:253] op_sel_hi:[1,0]
	v_pk_mul_f32 v[80:81], v[150:151], v[80:81]
	v_pk_mul_f32 v[82:83], v[152:153], v[82:83]
	v_cvt_pk_bf16_f32 v80, v80, v81
	v_cvt_pk_bf16_f32 v81, v82, v83
	global_store_dwordx2 v176, v[80:81], s[98:99] offset:288
	ds_read_b32 v246, v3 offset:4608
	ds_read_b32 v248, v3 offset:4672
	ds_read_b32 v250, v3 offset:4736
	ds_read_b32 v252, v3 offset:4800
	s_waitcnt lgkmcnt(3)
	s_add_u32 s98, s98, 0x28000
	s_addc_u32 s99, s99, 0
	v_pk_mul_f32 v[68:69], v[68:69], v[246:247] op_sel_hi:[1,0]
	v_pk_mul_f32 v[70:71], v[70:71], v[246:247] op_sel_hi:[1,0]
	v_pk_mul_f32 v[68:69], v[132:133], v[68:69]
	v_pk_mul_f32 v[70:71], v[134:135], v[70:71]
	v_cvt_pk_bf16_f32 v68, v68, v69
	v_cvt_pk_bf16_f32 v69, v70, v71
	global_store_dwordx2 v176, v[68:69], s[98:99] offset:0
	v_pk_mul_f32 v[60:61], v[60:61], v[246:247] op_sel_hi:[1,0]
	v_pk_mul_f32 v[62:63], v[62:63], v[246:247] op_sel_hi:[1,0]
	v_pk_mul_f32 v[60:61], v[140:141], v[60:61]
	v_pk_mul_f32 v[62:63], v[142:143], v[62:63]
	v_cvt_pk_bf16_f32 v60, v60, v61
	v_cvt_pk_bf16_f32 v61, v62, v63
	global_store_dwordx2 v176, v[60:61], s[98:99] offset:32
	v_pk_mul_f32 v[56:57], v[56:57], v[246:247] op_sel_hi:[1,0]
	v_pk_mul_f32 v[58:59], v[58:59], v[246:247] op_sel_hi:[1,0]
	v_pk_mul_f32 v[56:57], v[146:147], v[56:57]
	v_pk_mul_f32 v[58:59], v[148:149], v[58:59]
	v_cvt_pk_bf16_f32 v56, v56, v57
	v_cvt_pk_bf16_f32 v57, v58, v59
	global_store_dwordx2 v176, v[56:57], s[98:99] offset:256
	v_pk_mul_f32 v[52:53], v[52:53], v[246:247] op_sel_hi:[1,0]
	v_pk_mul_f32 v[54:55], v[54:55], v[246:247] op_sel_hi:[1,0]
	v_pk_mul_f32 v[52:53], v[150:151], v[52:53]
	v_pk_mul_f32 v[54:55], v[152:153], v[54:55]
	v_cvt_pk_bf16_f32 v52, v52, v53
	v_cvt_pk_bf16_f32 v53, v54, v55
	global_store_dwordx2 v176, v[52:53], s[98:99] offset:288
	s_waitcnt lgkmcnt(2)
; __device__ __forceinline__ unsigned pk2(float lo, float hi) { unsigned r; asm("v_cvt_pk_bf16_f32 %0, %1, %2" : "=v"(r) : "v"(lo), "v"(hi)); return r; }
;     __device__ __forceinline__ void fused(f32x4 (&acc)[2][2][4][2], const Unit& u, int wr, int wc, int fr, int fq, LAS unsigned char* lds, int wid, int lane) const {
;     ...
; #pragma unroll
;             for (int ai = 0; ai < 2; ++ai)
; #pragma unroll
;                 for (int m = 0; m < 4; ++m) { const int r = ai * HALF + wr * 64 + m * 16 + fr; const float rs = S[r]; bf16_t* hp = h + (size_t)(u.pm * BM + r) * D + col0;
; #pragma unroll
;                     for (int bj = 0; bj < 2; ++bj)
; #pragma unroll
;                         for (int n = 0; n < 2; ++n) { const f32x4 gv = *(const f32x4*)(g2 + col0 + bj * HALF + n * 16); const f32x4 o = acc[ai][bj][m][n] * rs * gv;
;                             u32x2 w; w.x = pk2(o[0], o[1]); w.y = pk2(o[2], o[3]); *(u32x2*)(hp + bj * HALF + n * 16) = w; }
;                     asm volatile("" ::: "memory"); }
	s_add_u32 s98, s98, 0x8000
	s_addc_u32 s99, s99, 0
	v_pk_mul_f32 v[48:49], v[48:49], v[248:249] op_sel_hi:[1,0]
	v_pk_mul_f32 v[50:51], v[50:51], v[248:249] op_sel_hi:[1,0]
	v_pk_mul_f32 v[48:49], v[132:133], v[48:49]
	v_pk_mul_f32 v[50:51], v[134:135], v[50:51]
	v_cvt_pk_bf16_f32 v48, v48, v49
	v_cvt_pk_bf16_f32 v49, v50, v51
	global_store_dwordx2 v176, v[48:49], s[98:99] offset:0
	v_pk_mul_f32 v[44:45], v[44:45], v[248:249] op_sel_hi:[1,0]
	v_pk_mul_f32 v[46:47], v[46:47], v[248:249] op_sel_hi:[1,0]
	v_pk_mul_f32 v[44:45], v[140:141], v[44:45]
	v_pk_mul_f32 v[46:47], v[142:143], v[46:47]
	v_cvt_pk_bf16_f32 v44, v44, v45
	v_cvt_pk_bf16_f32 v45, v46, v47
	global_store_dwordx2 v176, v[44:45], s[98:99] offset:32
	v_pk_mul_f32 v[40:41], v[40:41], v[248:249] op_sel_hi:[1,0]
	v_pk_mul_f32 v[42:43], v[42:43], v[248:249] op_sel_hi:[1,0]
	v_pk_mul_f32 v[40:41], v[146:147], v[40:41]
	v_pk_mul_f32 v[42:43], v[148:149], v[42:43]
	v_cvt_pk_bf16_f32 v40, v40, v41
	v_cvt_pk_bf16_f32 v41, v42, v43
	global_store_dwordx2 v176, v[40:41], s[98:99] offset:256
	v_pk_mul_f32 v[36:37], v[36:37], v[248:249] op_sel_hi:[1,0]
	v_pk_mul_f32 v[38:39], v[38:39], v[248:249] op_sel_hi:[1,0]
	v_pk_mul_f32 v[36:37], v[150:151], v[36:37]
	v_pk_mul_f32 v[38:39], v[152:153], v[38:39]
	v_cvt_pk_bf16_f32 v36, v36, v37
	v_cvt_pk_bf16_f32 v37, v38, v39
	global_store_dwordx2 v176, v[36:37], s[98:99] offset:288
	s_waitcnt lgkmcnt(1)
	s_add_u32 s98, s98, 0x8000
	s_addc_u32 s99, s99, 0
	v_pk_mul_f32 v[32:33], v[32:33], v[250:251] op_sel_hi:[1,0]
	v_pk_mul_f32 v[34:35], v[34:35], v[250:251] op_sel_hi:[1,0]
	v_pk_mul_f32 v[32:33], v[132:133], v[32:33]
	v_pk_mul_f32 v[34:35], v[134:135], v[34:35]
	v_cvt_pk_bf16_f32 v32, v32, v33
	v_cvt_pk_bf16_f32 v33, v34, v35
	global_store_dwordx2 v176, v[32:33], s[98:99] offset:0
	v_pk_mul_f32 v[28:29], v[28:29], v[250:251] op_sel_hi:[1,0]
	v_pk_mul_f32 v[30:31], v[30:31], v[250:251] op_sel_hi:[1,0]
	v_pk_mul_f32 v[28:29], v[140:141], v[28:29]
	v_pk_mul_f32 v[30:31], v[142:143], v[30:31]
	v_cvt_pk_bf16_f32 v28, v28, v29
	v_cvt_pk_bf16_f32 v29, v30, v31
	global_store_dwordx2 v176, v[28:29], s[98:99] offset:32
	v_pk_mul_f32 v[24:25], v[24:25], v[250:251] op_sel_hi:[1,0]
	v_pk_mul_f32 v[26:27], v[26:27], v[250:251] op_sel_hi:[1,0]
	v_pk_mul_f32 v[24:25], v[146:147], v[24:25]
	v_pk_mul_f32 v[26:27], v[148:149], v[26:27]
	v_cvt_pk_bf16_f32 v24, v24, v25
	v_cvt_pk_bf16_f32 v25, v26, v27
	global_store_dwordx2 v176, v[24:25], s[98:99] offset:256
	v_pk_mul_f32 v[20:21], v[20:21], v[250:251] op_sel_hi:[1,0]
	v_pk_mul_f32 v[22:23], v[22:23], v[250:251] op_sel_hi:[1,0]
	v_pk_mul_f32 v[20:21], v[150:151], v[20:21]
	v_pk_mul_f32 v[22:23], v[152:153], v[22:23]
	v_cvt_pk_bf16_f32 v20, v20, v21
	v_cvt_pk_bf16_f32 v21, v22, v23
	global_store_dwordx2 v176, v[20:21], s[98:99] offset:288
	s_waitcnt lgkmcnt(0)
	s_add_u32 s98, s98, 0x8000
	s_addc_u32 s99, s99, 0
	v_pk_mul_f32 v[16:17], v[16:17], v[252:253] op_sel_hi:[1,0]
	v_pk_mul_f32 v[18:19], v[18:19], v[252:253] op_sel_hi:[1,0]
	v_pk_mul_f32 v[16:17], v[132:133], v[16:17]
	v_pk_mul_f32 v[18:19], v[134:135], v[18:19]
	v_cvt_pk_bf16_f32 v16, v16, v17
	v_cvt_pk_bf16_f32 v17, v18, v19
	global_store_dwordx2 v176, v[16:17], s[98:99] offset:0
	v_pk_mul_f32 v[12:13], v[12:13], v[252:253] op_sel_hi:[1,0]
	v_pk_mul_f32 v[14:15], v[14:15], v[252:253] op_sel_hi:[1,0]
	v_pk_mul_f32 v[12:13], v[140:141], v[12:13]
	v_pk_mul_f32 v[14:15], v[142:143], v[14:15]
	v_cvt_pk_bf16_f32 v12, v12, v13
	v_cvt_pk_bf16_f32 v13, v14, v15
	global_store_dwordx2 v176, v[12:13], s[98:99] offset:32
	v_pk_mul_f32 v[8:9], v[8:9], v[252:253] op_sel_hi:[1,0]
	v_pk_mul_f32 v[10:11], v[10:11], v[252:253] op_sel_hi:[1,0]
	v_pk_mul_f32 v[8:9], v[146:147], v[8:9]
	v_pk_mul_f32 v[10:11], v[148:149], v[10:11]
	v_cvt_pk_bf16_f32 v8, v8, v9
	v_cvt_pk_bf16_f32 v9, v10, v11
	global_store_dwordx2 v176, v[8:9], s[98:99] offset:256
	v_pk_mul_f32 v[4:5], v[4:5], v[252:253] op_sel_hi:[1,0]
	v_pk_mul_f32 v[6:7], v[6:7], v[252:253] op_sel_hi:[1,0]
	v_pk_mul_f32 v[4:5], v[150:151], v[4:5]
	v_pk_mul_f32 v[6:7], v[152:153], v[6:7]
	v_cvt_pk_bf16_f32 v4, v4, v5
	v_cvt_pk_bf16_f32 v5, v6, v7
	global_store_dwordx2 v176, v[4:5], s[98:99] offset:288

; #define LAS __attribute__((address_space(3)))
;     __device__ __forceinline__ void fused(f32x4 (&acc)[2][2][4][2], const Unit& u, int wr, int wc, int fr, int fq, LAS unsigned char* lds, int wid, int lane) const {
;         const LAS float* S = (const LAS float*)(lds + 4096);
;         const int col0 = u.pn * BM + wc * 32 + 4 * fq;
;         stats(acc, u, wr, wc, fr, fq, lds, wid, lane, e1);
;         const bool defer = lin_in && !lin_out;
; #pragma unroll
;         for (int ai = 0; ai < 2; ++ai)
; #pragma unroll
;             for (int m = 0; m < 4; ++m) { const int r = ai * HALF + wr * 64 + m * 16 + fr; const float rs = S[r]; const int rb = ai * 8 + wr * 4 + m;
; #pragma unroll
;                 for (int bj = 0; bj < 2; ++bj)
; #pragma unroll
;                     for (int n = 0; n < 2; ++n) { const size_t orm = (size_t)(u.pm * BM + r) * D + col0 + bj * HALF + n * 16, oln = (size_t)(u.pm * BM + rb * 16 + 8 * bj + 2 * wc + n) * D + u.pn * BM + lane * 4;
;                         const f32x4 xv = *(const f32x4*)(xin + (lin_in ? oln : orm)); const f32x4 gv = *(const f32x4*)(g1 + col0 + bj * HALF + n * 16);
;                         const f32x4 o = xv + acc[ai][bj][m][n] * rs * gv; acc[ai][bj][m][n] = o; if (!defer) *(f32x4*)(x + (lin_out ? oln : orm)) = o; }
;                 asm volatile("" : "+v"(acc[ai][0][m][0]), "+v"(acc[ai][0][m][1]), "+v"(acc[ai][1][m][0]), "+v"(acc[ai][1][m][1]));
;                 asm volatile("" ::: "memory"); }
;         if (defer) {
.LBB0_490:
	s_or_b64 exec, exec, s[10:11]
	v_readlane_b32 s10, v255, 22
	s_lshl_b32 s20, s10, 10
	v_readlane_b32 s11, v255, 23
	s_ashr_i32 s21, s20, 31
	s_lshl_b32 s15, s14, 8
	s_lshl_b64 s[10:11], s[20:21], 2
	s_add_u32 s10, s30, s10
	s_addc_u32 s11, s31, s11
	s_cmp_gt_i32 s94, 21
	s_cselect_b64 s[24:25], -1, 0
	s_cmp_lt_i32 s94, 22
	s_cselect_b64 s[30:31], -1, 0
	s_lshl_b32 s16, s69, 1
	v_lshrrev_b32_e32 v0, 2, v156
	s_or_b32 s16, s41, s16
	v_and_b32_e32 v0, 12, v0
	s_add_i32 s28, s16, s39
	v_lshl_or_b32 v0, s69, 5, v0
	s_ashr_i32 s17, s15, 31
	s_ashr_i32 s29, s28, 31
	v_or_b32_e32 v0, s15, v0
	v_mov_b32_e32 v149, s17
	s_lshl_b64 s[16:17], s[28:29], 12
	s_waitcnt lgkmcnt(0)
	v_ashrrev_i32_e32 v1, 31, v0
	s_add_u32 s16, s18, s16
	s_waitcnt lgkmcnt(0)
	s_barrier
	v_lshl_add_u32 v3, v145, 2, 0
	v_lshrrev_b32_e32 v162, 8, v202
	v_bfe_u32 v163, v202, 6, 2
	v_and_b32_e32 v164, 15, v207
	v_lshrrev_b32_e32 v165, 4, v207
	s_lshl_b32 s16, s14, 10
	v_lshlrev_b32_e32 v166, 18, v162
	v_lshl_add_u32 v166, v163, 13, v166
	v_lshl_add_u32 v166, v207, 4, v166
	v_add_u32_e32 v166, s16, v166
	v_lshlrev_b32_e32 v156, 7, v163
	v_lshl_add_u32 v156, v165, 4, v156
	v_add_u32_e32 v156, s16, v156
	v_lshlrev_b32_e32 v157, 18, v162
	v_lshl_add_u32 v157, v164, 12, v157
	v_lshl_add_u32 v157, v163, 7, v157
	v_lshl_add_u32 v157, v165, 4, v157
	v_add_u32_e32 v157, s16, v157
	v_mov_b32_e32 v247, v166
	v_add_u32_e32 v249, 0x1000, v166
	v_add_u32_e32 v251, 0x8000, v166
	v_add_u32_e32 v253, 0x9000, v166
	s_lshl_b32 s16, s35, 20
	s_add_u32 s98, s18, s16
	s_addc_u32 s99, s19, 0
	s_mov_b32 s100, s98
	s_mov_b32 s101, s99
	s_and_b64 vcc, exec, s[24:25]
	s_cbranch_vccnz .Lepi6_defer
	global_load_dwordx4 v[132:135], v156, s[10:11] offset:0
	global_load_dwordx4 v[140:143], v156, s[10:11] offset:64
	global_load_dwordx4 v[148:151], v156, s[10:11] offset:512
	global_load_dwordx4 v[152:155], v156, s[10:11] offset:576
	global_load_dwordx4 v[162:165], v247, s[98:99]
	global_load_dwordx4 v[166:169], v249, s[98:99]
	global_load_dwordx4 v[170:173], v251, s[98:99]
	global_load_dwordx4 v[174:177], v253, s[98:99]
	s_add_u32 s98, s98, 0x10000
	s_addc_u32 s99, s99, 0
	global_load_dwordx4 v[178:181], v247, s[98:99]
	global_load_dwordx4 v[182:185], v249, s[98:99]
	global_load_dwordx4 v[186:189], v251, s[98:99]
	global_load_dwordx4 v[190:193], v253, s[98:99]
	s_add_u32 s98, s98, 0x10000
	s_addc_u32 s99, s99, 0
	global_load_dwordx4 v[194:197], v247, s[98:99]
	global_load_dwordx4 v[198:201], v249, s[98:99]
	global_load_dwordx4 v[214:217], v251, s[98:99]
	global_load_dwordx4 v[218:221], v253, s[98:99]
	s_add_u32 s98, s98, 0x10000
	s_addc_u32 s99, s99, 0
	global_load_dwordx4 v[222:225], v247, s[98:99]
	global_load_dwordx4 v[226:229], v249, s[98:99]
	global_load_dwordx4 v[230:233], v251, s[98:99]
	global_load_dwordx4 v[234:237], v253, s[98:99]
	ds_read_b32 v246, v3 offset:4096
	ds_read_b32 v248, v3 offset:4160
	ds_read_b32 v250, v3 offset:4224
	ds_read_b32 v252, v3 offset:4288
	s_waitcnt lgkmcnt(3)
	v_pk_mul_f32 v[100:101], v[100:101], v[246:247] op_sel_hi:[1,0]
	v_pk_mul_f32 v[102:103], v[102:103], v[246:247] op_sel_hi:[1,0]
	v_pk_mul_f32 v[108:109], v[108:109], v[246:247] op_sel_hi:[1,0]
	v_pk_mul_f32 v[110:111], v[110:111], v[246:247] op_sel_hi:[1,0]
	v_pk_mul_f32 v[116:117], v[116:117], v[246:247] op_sel_hi:[1,0]
	v_pk_mul_f32 v[118:119], v[118:119], v[246:247] op_sel_hi:[1,0]
	v_pk_mul_f32 v[124:125], v[124:125], v[246:247] op_sel_hi:[1,0]
	v_pk_mul_f32 v[126:127], v[126:127], v[246:247] op_sel_hi:[1,0]
	s_waitcnt lgkmcnt(2)
	v_pk_mul_f32 v[120:121], v[120:121], v[248:249] op_sel_hi:[1,0]
	v_pk_mul_f32 v[122:123], v[122:123], v[248:249] op_sel_hi:[1,0]
	v_pk_mul_f32 v[128:129], v[128:129], v[248:249] op_sel_hi:[1,0]
	v_pk_mul_f32 v[130:131], v[130:131], v[248:249] op_sel_hi:[1,0]
	v_pk_mul_f32 v[112:113], v[112:113], v[248:249] op_sel_hi:[1,0]
	v_pk_mul_f32 v[114:115], v[114:115], v[248:249] op_sel_hi:[1,0]
	v_pk_mul_f32 v[104:105], v[104:105], v[248:249] op_sel_hi:[1,0]
	v_pk_mul_f32 v[106:107], v[106:107], v[248:249] op_sel_hi:[1,0]
	s_waitcnt lgkmcnt(1)
	v_pk_mul_f32 v[96:97], v[96:97], v[250:251] op_sel_hi:[1,0]
	v_pk_mul_f32 v[98:99], v[98:99], v[250:251] op_sel_hi:[1,0]
	v_pk_mul_f32 v[92:93], v[92:93], v[250:251] op_sel_hi:[1,0]
	v_pk_mul_f32 v[94:95], v[94:95], v[250:251] op_sel_hi:[1,0]
	v_pk_mul_f32 v[88:89], v[88:89], v[250:251] op_sel_hi:[1,0]
	v_pk_mul_f32 v[90:91], v[90:91], v[250:251] op_sel_hi:[1,0]
	v_pk_mul_f32 v[84:85], v[84:85], v[250:251] op_sel_hi:[1,0]
	v_pk_mul_f32 v[86:87], v[86:87], v[250:251] op_sel_hi:[1,0]
	s_waitcnt lgkmcnt(0)
	v_pk_mul_f32 v[80:81], v[80:81], v[252:253] op_sel_hi:[1,0]
	v_pk_mul_f32 v[82:83], v[82:83], v[252:253] op_sel_hi:[1,0]
	v_pk_mul_f32 v[76:77], v[76:77], v[252:253] op_sel_hi:[1,0]
	v_pk_mul_f32 v[78:79], v[78:79], v[252:253] op_sel_hi:[1,0]
	v_pk_mul_f32 v[72:73], v[72:73], v[252:253] op_sel_hi:[1,0]
	v_pk_mul_f32 v[74:75], v[74:75], v[252:253] op_sel_hi:[1,0]
	v_pk_mul_f32 v[68:69], v[68:69], v[252:253] op_sel_hi:[1,0]
	v_pk_mul_f32 v[70:71], v[70:71], v[252:253] op_sel_hi:[1,0]
	ds_read_b32 v246, v3 offset:4608
	ds_read_b32 v248, v3 offset:4672
	ds_read_b32 v250, v3 offset:4736
	ds_read_b32 v252, v3 offset:4800
	s_waitcnt lgkmcnt(3)
	v_pk_mul_f32 v[64:65], v[64:65], v[246:247] op_sel_hi:[1,0]
	v_pk_mul_f32 v[66:67], v[66:67], v[246:247] op_sel_hi:[1,0]
	v_pk_mul_f32 v[60:61], v[60:61], v[246:247] op_sel_hi:[1,0]
	v_pk_mul_f32 v[62:63], v[62:63], v[246:247] op_sel_hi:[1,0]
	v_pk_mul_f32 v[56:57], v[56:57], v[246:247] op_sel_hi:[1,0]
	v_pk_mul_f32 v[58:59], v[58:59], v[246:247] op_sel_hi:[1,0]
	v_pk_mul_f32 v[52:53], v[52:53], v[246:247] op_sel_hi:[1,0]
	v_pk_mul_f32 v[54:55], v[54:55], v[246:247] op_sel_hi:[1,0]
	s_waitcnt lgkmcnt(2)
;     __device__ __forceinline__ void fused(f32x4 (&acc)[2][2][4][2], const Unit& u, int wr, int wc, int fr, int fq, LAS unsigned char* lds, int wid, int lane) const {
;     ...
;         for (int ai = 0; ai < 2; ++ai)
; #pragma unroll
;             for (int m = 0; m < 4; ++m) { const int r = ai * HALF + wr * 64 + m * 16 + fr; const float rs = S[r]; const int rb = ai * 8 + wr * 4 + m;
; #pragma unroll
;                 for (int bj = 0; bj < 2; ++bj)
; #pragma unroll
;                     for (int n = 0; n < 2; ++n) { const size_t orm = (size_t)(u.pm * BM + r) * D + col0 + bj * HALF + n * 16, oln = (size_t)(u.pm * BM + rb * 16 + 8 * bj + 2 * wc + n) * D + u.pn * BM + lane * 4;
;                         const f32x4 xv = *(const f32x4*)(xin + (lin_in ? oln : orm)); const f32x4 gv = *(const f32x4*)(g1 + col0 + bj * HALF + n * 16);
;                         const f32x4 o = xv + acc[ai][bj][m][n] * rs * gv; acc[ai][bj][m][n] = o; if (!defer) *(f32x4*)(x + (lin_out ? oln : orm)) = o; }
;                 asm volatile("" : "+v"(acc[ai][0][m][0]), "+v"(acc[ai][0][m][1]), "+v"(acc[ai][1][m][0]), "+v"(acc[ai][1][m][1]));
;                 asm volatile("" ::: "memory"); }
	v_pk_mul_f32 v[48:49], v[48:49], v[248:249] op_sel_hi:[1,0]
	v_pk_mul_f32 v[50:51], v[50:51], v[248:249] op_sel_hi:[1,0]
	v_pk_mul_f32 v[44:45], v[44:45], v[248:249] op_sel_hi:[1,0]
	v_pk_mul_f32 v[46:47], v[46:47], v[248:249] op_sel_hi:[1,0]
	v_pk_mul_f32 v[40:41], v[40:41], v[248:249] op_sel_hi:[1,0]
	v_pk_mul_f32 v[42:43], v[42:43], v[248:249] op_sel_hi:[1,0]
	v_pk_mul_f32 v[36:37], v[36:37], v[248:249] op_sel_hi:[1,0]
	v_pk_mul_f32 v[38:39], v[38:39], v[248:249] op_sel_hi:[1,0]
	s_waitcnt lgkmcnt(1)
	v_pk_mul_f32 v[32:33], v[32:33], v[250:251] op_sel_hi:[1,0]
	v_pk_mul_f32 v[34:35], v[34:35], v[250:251] op_sel_hi:[1,0]
	v_pk_mul_f32 v[28:29], v[28:29], v[250:251] op_sel_hi:[1,0]
	v_pk_mul_f32 v[30:31], v[30:31], v[250:251] op_sel_hi:[1,0]
	v_pk_mul_f32 v[24:25], v[24:25], v[250:251] op_sel_hi:[1,0]
	v_pk_mul_f32 v[26:27], v[26:27], v[250:251] op_sel_hi:[1,0]
	v_pk_mul_f32 v[20:21], v[20:21], v[250:251] op_sel_hi:[1,0]
	v_pk_mul_f32 v[22:23], v[22:23], v[250:251] op_sel_hi:[1,0]
	s_waitcnt lgkmcnt(0)
	v_pk_mul_f32 v[16:17], v[16:17], v[252:253] op_sel_hi:[1,0]
	v_pk_mul_f32 v[18:19], v[18:19], v[252:253] op_sel_hi:[1,0]
	v_pk_mul_f32 v[12:13], v[12:13], v[252:253] op_sel_hi:[1,0]
	v_pk_mul_f32 v[14:15], v[14:15], v[252:253] op_sel_hi:[1,0]
	v_pk_mul_f32 v[8:9], v[8:9], v[252:253] op_sel_hi:[1,0]
	v_pk_mul_f32 v[10:11], v[10:11], v[252:253] op_sel_hi:[1,0]
	v_pk_mul_f32 v[4:5], v[4:5], v[252:253] op_sel_hi:[1,0]
	v_pk_mul_f32 v[6:7], v[6:7], v[252:253] op_sel_hi:[1,0]
	s_waitcnt vmcnt(15)
	v_pk_fma_f32 v[100:101], v[132:133], v[100:101], v[162:163]
	v_pk_fma_f32 v[102:103], v[134:135], v[102:103], v[164:165]
	global_store_dwordx4 v247, v[100:103], s[100:101]
	s_add_u32 s98, s98, 0x50000
	s_addc_u32 s99, s99, 0
	global_load_dwordx4 v[162:165], v247, s[98:99]
	s_waitcnt vmcnt(16)
	v_pk_fma_f32 v[108:109], v[140:141], v[108:109], v[166:167]
	v_pk_fma_f32 v[110:111], v[142:143], v[110:111], v[168:169]
	global_store_dwordx4 v249, v[108:111], s[100:101]
	global_load_dwordx4 v[166:169], v249, s[98:99]
	s_waitcnt vmcnt(17)
	v_pk_fma_f32 v[116:117], v[148:149], v[116:117], v[170:171]
	v_pk_fma_f32 v[118:119], v[150:151], v[118:119], v[172:173]
	global_store_dwordx4 v251, v[116:119], s[100:101]
	global_load_dwordx4 v[170:173], v251, s[98:99]
	s_waitcnt vmcnt(18)
	v_pk_fma_f32 v[124:125], v[152:153], v[124:125], v[174:175]
	v_pk_fma_f32 v[126:127], v[154:155], v[126:127], v[176:177]
	global_store_dwordx4 v253, v[124:127], s[100:101]
	global_load_dwordx4 v[174:177], v253, s[98:99]
	s_waitcnt vmcnt(19)
	v_pk_fma_f32 v[120:121], v[132:133], v[120:121], v[178:179]
	v_pk_fma_f32 v[122:123], v[134:135], v[122:123], v[180:181]
	s_add_u32 s100, s100, 0x10000
	s_addc_u32 s101, s101, 0
	global_store_dwordx4 v247, v[120:123], s[100:101]
	s_add_u32 s98, s98, 0x10000
	s_addc_u32 s99, s99, 0
	global_load_dwordx4 v[178:181], v247, s[98:99]
	s_waitcnt vmcnt(20)
	v_pk_fma_f32 v[128:129], v[140:141], v[128:129], v[182:183]
	v_pk_fma_f32 v[130:131], v[142:143], v[130:131], v[184:185]
	global_store_dwordx4 v249, v[128:131], s[100:101]
	global_load_dwordx4 v[182:185], v249, s[98:99]
	s_waitcnt vmcnt(21)
	v_pk_fma_f32 v[112:113], v[148:149], v[112:113], v[186:187]
	v_pk_fma_f32 v[114:115], v[150:151], v[114:115], v[188:189]
	global_store_dwordx4 v251, v[112:115], s[100:101]
	global_load_dwordx4 v[186:189], v251, s[98:99]
	s_waitcnt vmcnt(22)
	v_pk_fma_f32 v[104:105], v[152:153], v[104:105], v[190:191]
	v_pk_fma_f32 v[106:107], v[154:155], v[106:107], v[192:193]
	global_store_dwordx4 v253, v[104:107], s[100:101]
	global_load_dwordx4 v[190:193], v253, s[98:99]
	s_waitcnt vmcnt(23)
	v_pk_fma_f32 v[96:97], v[132:133], v[96:97], v[194:195]
	v_pk_fma_f32 v[98:99], v[134:135], v[98:99], v[196:197]
	s_add_u32 s100, s100, 0x10000
	s_addc_u32 s101, s101, 0
	global_store_dwordx4 v247, v[96:99], s[100:101]
	s_add_u32 s98, s98, 0x10000
	s_addc_u32 s99, s99, 0
	global_load_dwordx4 v[194:197], v247, s[98:99]
	s_waitcnt vmcnt(24)
	v_pk_fma_f32 v[92:93], v[140:141], v[92:93], v[198:199]
	v_pk_fma_f32 v[94:95], v[142:143], v[94:95], v[200:201]
	global_store_dwordx4 v249, v[92:95], s[100:101]
	global_load_dwordx4 v[198:201], v249, s[98:99]
	s_waitcnt vmcnt(25)
	v_pk_fma_f32 v[88:89], v[148:149], v[88:89], v[214:215]
	v_pk_fma_f32 v[90:91], v[150:151], v[90:91], v[216:217]
	global_store_dwordx4 v251, v[88:91], s[100:101]
	global_load_dwordx4 v[214:217], v251, s[98:99]
	s_waitcnt vmcnt(26)
	v_pk_fma_f32 v[84:85], v[152:153], v[84:85], v[218:219]
	v_pk_fma_f32 v[86:87], v[154:155], v[86:87], v[220:221]
	global_store_dwordx4 v253, v[84:87], s[100:101]
	global_load_dwordx4 v[218:221], v253, s[98:99]
	s_waitcnt vmcnt(27)
	v_pk_fma_f32 v[80:81], v[132:133], v[80:81], v[222:223]
	v_pk_fma_f32 v[82:83], v[134:135], v[82:83], v[224:225]
	s_add_u32 s100, s100, 0x10000
	s_addc_u32 s101, s101, 0
	global_store_dwordx4 v247, v[80:83], s[100:101]
	s_add_u32 s98, s98, 0x10000
	s_addc_u32 s99, s99, 0
	global_load_dwordx4 v[222:225], v247, s[98:99]
	s_waitcnt vmcnt(28)
	v_pk_fma_f32 v[76:77], v[140:141], v[76:77], v[226:227]
	v_pk_fma_f32 v[78:79], v[142:143], v[78:79], v[228:229]
	global_store_dwordx4 v249, v[76:79], s[100:101]
	global_load_dwordx4 v[226:229], v249, s[98:99]
	s_waitcnt vmcnt(29)
	v_pk_fma_f32 v[72:73], v[148:149], v[72:73], v[230:231]
	v_pk_fma_f32 v[74:75], v[150:151], v[74:75], v[232:233]
	global_store_dwordx4 v251, v[72:75], s[100:101]
	global_load_dwordx4 v[230:233], v251, s[98:99]
	s_waitcnt vmcnt(30)
	v_pk_fma_f32 v[68:69], v[152:153], v[68:69], v[234:235]
	v_pk_fma_f32 v[70:71], v[154:155], v[70:71], v[236:237]
	global_store_dwordx4 v253, v[68:71], s[100:101]
	global_load_dwordx4 v[234:237], v253, s[98:99]
	s_waitcnt vmcnt(30)
;     __device__ __forceinline__ void fused(f32x4 (&acc)[2][2][4][2], const Unit& u, int wr, int wc, int fr, int fq, LAS unsigned char* lds, int wid, int lane) const {
;     ...
;         for (int ai = 0; ai < 2; ++ai)
; #pragma unroll
;             for (int m = 0; m < 4; ++m) { const int r = ai * HALF + wr * 64 + m * 16 + fr; const float rs = S[r]; const int rb = ai * 8 + wr * 4 + m;
; #pragma unroll
;                 for (int bj = 0; bj < 2; ++bj)
; #pragma unroll
;                     for (int n = 0; n < 2; ++n) { const size_t orm = (size_t)(u.pm * BM + r) * D + col0 + bj * HALF + n * 16, oln = (size_t)(u.pm * BM + rb * 16 + 8 * bj + 2 * wc + n) * D + u.pn * BM + lane * 4;
;                         const f32x4 xv = *(const f32x4*)(xin + (lin_in ? oln : orm)); const f32x4 gv = *(const f32x4*)(g1 + col0 + bj * HALF + n * 16);
;                         const f32x4 o = xv + acc[ai][bj][m][n] * rs * gv; acc[ai][bj][m][n] = o; if (!defer) *(f32x4*)(x + (lin_out ? oln : orm)) = o; }
;                 asm volatile("" : "+v"(acc[ai][0][m][0]), "+v"(acc[ai][0][m][1]), "+v"(acc[ai][1][m][0]), "+v"(acc[ai][1][m][1]));
;                 asm volatile("" ::: "memory"); }
;         if (defer) {
	v_pk_fma_f32 v[64:65], v[132:133], v[64:65], v[162:163]
	v_pk_fma_f32 v[66:67], v[134:135], v[66:67], v[164:165]
	s_add_u32 s100, s100, 0x50000
	s_addc_u32 s101, s101, 0
	global_store_dwordx4 v247, v[64:67], s[100:101]
	s_waitcnt vmcnt(29)
	v_pk_fma_f32 v[60:61], v[140:141], v[60:61], v[166:167]
	v_pk_fma_f32 v[62:63], v[142:143], v[62:63], v[168:169]
	global_store_dwordx4 v249, v[60:63], s[100:101]
	s_waitcnt vmcnt(28)
	v_pk_fma_f32 v[56:57], v[148:149], v[56:57], v[170:171]
	v_pk_fma_f32 v[58:59], v[150:151], v[58:59], v[172:173]
	global_store_dwordx4 v251, v[56:59], s[100:101]
	s_waitcnt vmcnt(27)
	v_pk_fma_f32 v[52:53], v[152:153], v[52:53], v[174:175]
	v_pk_fma_f32 v[54:55], v[154:155], v[54:55], v[176:177]
	global_store_dwordx4 v253, v[52:55], s[100:101]
	s_waitcnt vmcnt(26)
	v_pk_fma_f32 v[48:49], v[132:133], v[48:49], v[178:179]
	v_pk_fma_f32 v[50:51], v[134:135], v[50:51], v[180:181]
	s_add_u32 s100, s100, 0x10000
	s_addc_u32 s101, s101, 0
	global_store_dwordx4 v247, v[48:51], s[100:101]
	s_waitcnt vmcnt(25)
	v_pk_fma_f32 v[44:45], v[140:141], v[44:45], v[182:183]
	v_pk_fma_f32 v[46:47], v[142:143], v[46:47], v[184:185]
	global_store_dwordx4 v249, v[44:47], s[100:101]
	s_waitcnt vmcnt(24)
	v_pk_fma_f32 v[40:41], v[148:149], v[40:41], v[186:187]
	v_pk_fma_f32 v[42:43], v[150:151], v[42:43], v[188:189]
	global_store_dwordx4 v251, v[40:43], s[100:101]
	s_waitcnt vmcnt(23)
	v_pk_fma_f32 v[36:37], v[152:153], v[36:37], v[190:191]
	v_pk_fma_f32 v[38:39], v[154:155], v[38:39], v[192:193]
	global_store_dwordx4 v253, v[36:39], s[100:101]
	s_waitcnt vmcnt(22)
	v_pk_fma_f32 v[32:33], v[132:133], v[32:33], v[194:195]
	v_pk_fma_f32 v[34:35], v[134:135], v[34:35], v[196:197]
	s_add_u32 s100, s100, 0x10000
	s_addc_u32 s101, s101, 0
	global_store_dwordx4 v247, v[32:35], s[100:101]
	s_waitcnt vmcnt(21)
	v_pk_fma_f32 v[28:29], v[140:141], v[28:29], v[198:199]
	v_pk_fma_f32 v[30:31], v[142:143], v[30:31], v[200:201]
	global_store_dwordx4 v249, v[28:31], s[100:101]
	s_waitcnt vmcnt(20)
	v_pk_fma_f32 v[24:25], v[148:149], v[24:25], v[214:215]
	v_pk_fma_f32 v[26:27], v[150:151], v[26:27], v[216:217]
	global_store_dwordx4 v251, v[24:27], s[100:101]
	s_waitcnt vmcnt(19)
	v_pk_fma_f32 v[20:21], v[152:153], v[20:21], v[218:219]
	v_pk_fma_f32 v[22:23], v[154:155], v[22:23], v[220:221]
	global_store_dwordx4 v253, v[20:23], s[100:101]
	s_waitcnt vmcnt(18)
	v_pk_fma_f32 v[16:17], v[132:133], v[16:17], v[222:223]
	v_pk_fma_f32 v[18:19], v[134:135], v[18:19], v[224:225]
	s_add_u32 s100, s100, 0x10000
	s_addc_u32 s101, s101, 0
	global_store_dwordx4 v247, v[16:19], s[100:101]
	s_waitcnt vmcnt(17)
	v_pk_fma_f32 v[12:13], v[140:141], v[12:13], v[226:227]
	v_pk_fma_f32 v[14:15], v[142:143], v[14:15], v[228:229]
	global_store_dwordx4 v249, v[12:15], s[100:101]
	s_waitcnt vmcnt(16)
	v_pk_fma_f32 v[8:9], v[148:149], v[8:9], v[230:231]
	v_pk_fma_f32 v[10:11], v[150:151], v[10:11], v[232:233]
	global_store_dwordx4 v251, v[8:11], s[100:101]
	s_waitcnt vmcnt(15)
	v_pk_fma_f32 v[4:5], v[152:153], v[4:5], v[234:235]
	v_pk_fma_f32 v[6:7], v[154:155], v[6:7], v[236:237]
	global_store_dwordx4 v253, v[4:7], s[100:101]
	s_branch .LBB0_556
.Lepi6_defer:
	global_load_dwordx4 v[132:135], v156, s[10:11] offset:0
	global_load_dwordx4 v[140:143], v156, s[10:11] offset:64
	global_load_dwordx4 v[148:151], v156, s[10:11] offset:512
	global_load_dwordx4 v[152:155], v156, s[10:11] offset:576
	global_load_dwordx4 v[162:165], v247, s[98:99]
	global_load_dwordx4 v[166:169], v249, s[98:99]
	global_load_dwordx4 v[170:173], v251, s[98:99]
	global_load_dwordx4 v[174:177], v253, s[98:99]
	s_add_u32 s98, s98, 0x10000
	s_addc_u32 s99, s99, 0
	global_load_dwordx4 v[178:181], v247, s[98:99]
	global_load_dwordx4 v[182:185], v249, s[98:99]
	global_load_dwordx4 v[186:189], v251, s[98:99]
	global_load_dwordx4 v[190:193], v253, s[98:99]
	s_add_u32 s98, s98, 0x10000
	s_addc_u32 s99, s99, 0
	global_load_dwordx4 v[194:197], v247, s[98:99]
	global_load_dwordx4 v[198:201], v249, s[98:99]
	global_load_dwordx4 v[214:217], v251, s[98:99]
	global_load_dwordx4 v[218:221], v253, s[98:99]
	s_add_u32 s98, s98, 0x10000
	s_addc_u32 s99, s99, 0
	global_load_dwordx4 v[222:225], v247, s[98:99]
	global_load_dwordx4 v[226:229], v249, s[98:99]
	global_load_dwordx4 v[230:233], v251, s[98:99]
	global_load_dwordx4 v[234:237], v253, s[98:99]
	ds_read_b32 v246, v3 offset:4096
	ds_read_b32 v248, v3 offset:4160
	ds_read_b32 v250, v3 offset:4224
	ds_read_b32 v252, v3 offset:4288
	s_waitcnt lgkmcnt(3)
	v_pk_mul_f32 v[100:101], v[100:101], v[246:247] op_sel_hi:[1,0]
	v_pk_mul_f32 v[102:103], v[102:103], v[246:247] op_sel_hi:[1,0]
	v_pk_mul_f32 v[108:109], v[108:109], v[246:247] op_sel_hi:[1,0]
	v_pk_mul_f32 v[110:111], v[110:111], v[246:247] op_sel_hi:[1,0]
	v_pk_mul_f32 v[116:117], v[116:117], v[246:247] op_sel_hi:[1,0]
	v_pk_mul_f32 v[118:119], v[118:119], v[246:247] op_sel_hi:[1,0]
	v_pk_mul_f32 v[124:125], v[124:125], v[246:247] op_sel_hi:[1,0]
	v_pk_mul_f32 v[126:127], v[126:127], v[246:247] op_sel_hi:[1,0]
	s_waitcnt lgkmcnt(2)
	v_pk_mul_f32 v[120:121], v[120:121], v[248:249] op_sel_hi:[1,0]
	v_pk_mul_f32 v[122:123], v[122:123], v[248:249] op_sel_hi:[1,0]
	v_pk_mul_f32 v[128:129], v[128:129], v[248:249] op_sel_hi:[1,0]
	v_pk_mul_f32 v[130:131], v[130:131], v[248:249] op_sel_hi:[1,0]
	v_pk_mul_f32 v[112:113], v[112:113], v[248:249] op_sel_hi:[1,0]
	v_pk_mul_f32 v[114:115], v[114:115], v[248:249] op_sel_hi:[1,0]
	v_pk_mul_f32 v[104:105], v[104:105], v[248:249] op_sel_hi:[1,0]
	v_pk_mul_f32 v[106:107], v[106:107], v[248:249] op_sel_hi:[1,0]
	s_waitcnt lgkmcnt(1)
;     __device__ __forceinline__ void fused(f32x4 (&acc)[2][2][4][2], const Unit& u, int wr, int wc, int fr, int fq, LAS unsigned char* lds, int wid, int lane) const {
;     ...
;         for (int ai = 0; ai < 2; ++ai)
; #pragma unroll
;             for (int m = 0; m < 4; ++m) { const int r = ai * HALF + wr * 64 + m * 16 + fr; const float rs = S[r]; const int rb = ai * 8 + wr * 4 + m;
; #pragma unroll
;                 for (int bj = 0; bj < 2; ++bj)
; #pragma unroll
;                     for (int n = 0; n < 2; ++n) { const size_t orm = (size_t)(u.pm * BM + r) * D + col0 + bj * HALF + n * 16, oln = (size_t)(u.pm * BM + rb * 16 + 8 * bj + 2 * wc + n) * D + u.pn * BM + lane * 4;
;                         const f32x4 xv = *(const f32x4*)(xin + (lin_in ? oln : orm)); const f32x4 gv = *(const f32x4*)(g1 + col0 + bj * HALF + n * 16);
;                         const f32x4 o = xv + acc[ai][bj][m][n] * rs * gv; acc[ai][bj][m][n] = o; if (!defer) *(f32x4*)(x + (lin_out ? oln : orm)) = o; }
;                 asm volatile("" : "+v"(acc[ai][0][m][0]), "+v"(acc[ai][0][m][1]), "+v"(acc[ai][1][m][0]), "+v"(acc[ai][1][m][1]));
;                 asm volatile("" ::: "memory"); }
	v_pk_mul_f32 v[96:97], v[96:97], v[250:251] op_sel_hi:[1,0]
	v_pk_mul_f32 v[98:99], v[98:99], v[250:251] op_sel_hi:[1,0]
	v_pk_mul_f32 v[92:93], v[92:93], v[250:251] op_sel_hi:[1,0]
	v_pk_mul_f32 v[94:95], v[94:95], v[250:251] op_sel_hi:[1,0]
	v_pk_mul_f32 v[88:89], v[88:89], v[250:251] op_sel_hi:[1,0]
	v_pk_mul_f32 v[90:91], v[90:91], v[250:251] op_sel_hi:[1,0]
	v_pk_mul_f32 v[84:85], v[84:85], v[250:251] op_sel_hi:[1,0]
	v_pk_mul_f32 v[86:87], v[86:87], v[250:251] op_sel_hi:[1,0]
	s_waitcnt lgkmcnt(0)
	v_pk_mul_f32 v[80:81], v[80:81], v[252:253] op_sel_hi:[1,0]
	v_pk_mul_f32 v[82:83], v[82:83], v[252:253] op_sel_hi:[1,0]
	v_pk_mul_f32 v[76:77], v[76:77], v[252:253] op_sel_hi:[1,0]
	v_pk_mul_f32 v[78:79], v[78:79], v[252:253] op_sel_hi:[1,0]
	v_pk_mul_f32 v[72:73], v[72:73], v[252:253] op_sel_hi:[1,0]
	v_pk_mul_f32 v[74:75], v[74:75], v[252:253] op_sel_hi:[1,0]
	v_pk_mul_f32 v[68:69], v[68:69], v[252:253] op_sel_hi:[1,0]
	v_pk_mul_f32 v[70:71], v[70:71], v[252:253] op_sel_hi:[1,0]
	ds_read_b32 v246, v3 offset:4608
	ds_read_b32 v248, v3 offset:4672
	ds_read_b32 v250, v3 offset:4736
	ds_read_b32 v252, v3 offset:4800
	s_waitcnt lgkmcnt(3)
	v_pk_mul_f32 v[64:65], v[64:65], v[246:247] op_sel_hi:[1,0]
	v_pk_mul_f32 v[66:67], v[66:67], v[246:247] op_sel_hi:[1,0]
	v_pk_mul_f32 v[60:61], v[60:61], v[246:247] op_sel_hi:[1,0]
	v_pk_mul_f32 v[62:63], v[62:63], v[246:247] op_sel_hi:[1,0]
	v_pk_mul_f32 v[56:57], v[56:57], v[246:247] op_sel_hi:[1,0]
	v_pk_mul_f32 v[58:59], v[58:59], v[246:247] op_sel_hi:[1,0]
	v_pk_mul_f32 v[52:53], v[52:53], v[246:247] op_sel_hi:[1,0]
	v_pk_mul_f32 v[54:55], v[54:55], v[246:247] op_sel_hi:[1,0]
	s_waitcnt lgkmcnt(2)
	v_pk_mul_f32 v[48:49], v[48:49], v[248:249] op_sel_hi:[1,0]
	v_pk_mul_f32 v[50:51], v[50:51], v[248:249] op_sel_hi:[1,0]
	v_pk_mul_f32 v[44:45], v[44:45], v[248:249] op_sel_hi:[1,0]
	v_pk_mul_f32 v[46:47], v[46:47], v[248:249] op_sel_hi:[1,0]
	v_pk_mul_f32 v[40:41], v[40:41], v[248:249] op_sel_hi:[1,0]
	v_pk_mul_f32 v[42:43], v[42:43], v[248:249] op_sel_hi:[1,0]
	v_pk_mul_f32 v[36:37], v[36:37], v[248:249] op_sel_hi:[1,0]
	v_pk_mul_f32 v[38:39], v[38:39], v[248:249] op_sel_hi:[1,0]
	s_waitcnt lgkmcnt(1)
	v_pk_mul_f32 v[32:33], v[32:33], v[250:251] op_sel_hi:[1,0]
	v_pk_mul_f32 v[34:35], v[34:35], v[250:251] op_sel_hi:[1,0]
	v_pk_mul_f32 v[28:29], v[28:29], v[250:251] op_sel_hi:[1,0]
	v_pk_mul_f32 v[30:31], v[30:31], v[250:251] op_sel_hi:[1,0]
	v_pk_mul_f32 v[24:25], v[24:25], v[250:251] op_sel_hi:[1,0]
	v_pk_mul_f32 v[26:27], v[26:27], v[250:251] op_sel_hi:[1,0]
	v_pk_mul_f32 v[20:21], v[20:21], v[250:251] op_sel_hi:[1,0]
	v_pk_mul_f32 v[22:23], v[22:23], v[250:251] op_sel_hi:[1,0]
	s_waitcnt lgkmcnt(0)
	v_pk_mul_f32 v[16:17], v[16:17], v[252:253] op_sel_hi:[1,0]
	v_pk_mul_f32 v[18:19], v[18:19], v[252:253] op_sel_hi:[1,0]
	v_pk_mul_f32 v[12:13], v[12:13], v[252:253] op_sel_hi:[1,0]
	v_pk_mul_f32 v[14:15], v[14:15], v[252:253] op_sel_hi:[1,0]
	v_pk_mul_f32 v[8:9], v[8:9], v[252:253] op_sel_hi:[1,0]
	v_pk_mul_f32 v[10:11], v[10:11], v[252:253] op_sel_hi:[1,0]
	v_pk_mul_f32 v[4:5], v[4:5], v[252:253] op_sel_hi:[1,0]
	v_pk_mul_f32 v[6:7], v[6:7], v[252:253] op_sel_hi:[1,0]
	s_waitcnt vmcnt(15)
	v_pk_fma_f32 v[100:101], v[132:133], v[100:101], v[162:163]
	v_pk_fma_f32 v[102:103], v[134:135], v[102:103], v[164:165]
	s_add_u32 s98, s98, 0x50000
	s_addc_u32 s99, s99, 0
	global_load_dwordx4 v[162:165], v247, s[98:99]
	s_waitcnt vmcnt(15)
	v_pk_fma_f32 v[108:109], v[140:141], v[108:109], v[166:167]
	v_pk_fma_f32 v[110:111], v[142:143], v[110:111], v[168:169]
	global_load_dwordx4 v[166:169], v249, s[98:99]
	s_waitcnt vmcnt(15)
	v_pk_fma_f32 v[116:117], v[148:149], v[116:117], v[170:171]
	v_pk_fma_f32 v[118:119], v[150:151], v[118:119], v[172:173]
	global_load_dwordx4 v[170:173], v251, s[98:99]
	s_waitcnt vmcnt(15)
	v_pk_fma_f32 v[124:125], v[152:153], v[124:125], v[174:175]
	v_pk_fma_f32 v[126:127], v[154:155], v[126:127], v[176:177]
	global_load_dwordx4 v[174:177], v253, s[98:99]
	s_waitcnt vmcnt(15)
	v_pk_fma_f32 v[120:121], v[132:133], v[120:121], v[178:179]
	v_pk_fma_f32 v[122:123], v[134:135], v[122:123], v[180:181]
	s_add_u32 s98, s98, 0x10000
	s_addc_u32 s99, s99, 0
	global_load_dwordx4 v[178:181], v247, s[98:99]
	s_waitcnt vmcnt(15)
	v_pk_fma_f32 v[128:129], v[140:141], v[128:129], v[182:183]
	v_pk_fma_f32 v[130:131], v[142:143], v[130:131], v[184:185]
	global_load_dwordx4 v[182:185], v249, s[98:99]
	s_waitcnt vmcnt(15)
	v_pk_fma_f32 v[112:113], v[148:149], v[112:113], v[186:187]
	v_pk_fma_f32 v[114:115], v[150:151], v[114:115], v[188:189]
	global_load_dwordx4 v[186:189], v251, s[98:99]
	s_waitcnt vmcnt(15)
	v_pk_fma_f32 v[104:105], v[152:153], v[104:105], v[190:191]
	v_pk_fma_f32 v[106:107], v[154:155], v[106:107], v[192:193]
	global_load_dwordx4 v[190:193], v253, s[98:99]
	s_waitcnt vmcnt(15)
	v_pk_fma_f32 v[96:97], v[132:133], v[96:97], v[194:195]
	v_pk_fma_f32 v[98:99], v[134:135], v[98:99], v[196:197]
	s_add_u32 s98, s98, 0x10000
	s_addc_u32 s99, s99, 0
	global_load_dwordx4 v[194:197], v247, s[98:99]
	s_waitcnt vmcnt(15)
	v_pk_fma_f32 v[92:93], v[140:141], v[92:93], v[198:199]
	v_pk_fma_f32 v[94:95], v[142:143], v[94:95], v[200:201]
	global_load_dwordx4 v[198:201], v249, s[98:99]
	s_waitcnt vmcnt(15)
;     __device__ __forceinline__ void fused(f32x4 (&acc)[2][2][4][2], const Unit& u, int wr, int wc, int fr, int fq, LAS unsigned char* lds, int wid, int lane) const {
;     ...
;         for (int ai = 0; ai < 2; ++ai)
; #pragma unroll
;             for (int m = 0; m < 4; ++m) { const int r = ai * HALF + wr * 64 + m * 16 + fr; const float rs = S[r]; const int rb = ai * 8 + wr * 4 + m;
; #pragma unroll
;                 for (int bj = 0; bj < 2; ++bj)
; #pragma unroll
;                     for (int n = 0; n < 2; ++n) { const size_t orm = (size_t)(u.pm * BM + r) * D + col0 + bj * HALF + n * 16, oln = (size_t)(u.pm * BM + rb * 16 + 8 * bj + 2 * wc + n) * D + u.pn * BM + lane * 4;
;                         const f32x4 xv = *(const f32x4*)(xin + (lin_in ? oln : orm)); const f32x4 gv = *(const f32x4*)(g1 + col0 + bj * HALF + n * 16);
;                         const f32x4 o = xv + acc[ai][bj][m][n] * rs * gv; acc[ai][bj][m][n] = o; if (!defer) *(f32x4*)(x + (lin_out ? oln : orm)) = o; }
;                 asm volatile("" : "+v"(acc[ai][0][m][0]), "+v"(acc[ai][0][m][1]), "+v"(acc[ai][1][m][0]), "+v"(acc[ai][1][m][1]));
;                 asm volatile("" ::: "memory"); }
;         if (defer) {
;             asm volatile("s_waitcnt vmcnt(0)" ::: "memory"); __builtin_amdgcn_s_barrier(); asm volatile("" ::: "memory");
; #pragma unroll
;             for (int ai = 0; ai < 2; ++ai)
; #pragma unroll
;                 for (int m = 0; m < 4; ++m) { const int r = ai * HALF + wr * 64 + m * 16 + fr; float* xp = x + (size_t)(u.pm * BM + r) * D + col0;
; #pragma unroll
;                     for (int bj = 0; bj < 2; ++bj)
; #pragma unroll
;                         for (int n = 0; n < 2; ++n) *(f32x4*)(xp + bj * HALF + n * 16) = acc[ai][bj][m][n]; }
;         }
	v_pk_fma_f32 v[88:89], v[148:149], v[88:89], v[214:215]
	v_pk_fma_f32 v[90:91], v[150:151], v[90:91], v[216:217]
	global_load_dwordx4 v[214:217], v251, s[98:99]
	s_waitcnt vmcnt(15)
	v_pk_fma_f32 v[84:85], v[152:153], v[84:85], v[218:219]
	v_pk_fma_f32 v[86:87], v[154:155], v[86:87], v[220:221]
	global_load_dwordx4 v[218:221], v253, s[98:99]
	s_waitcnt vmcnt(15)
	v_pk_fma_f32 v[80:81], v[132:133], v[80:81], v[222:223]
	v_pk_fma_f32 v[82:83], v[134:135], v[82:83], v[224:225]
	s_add_u32 s98, s98, 0x10000
	s_addc_u32 s99, s99, 0
	global_load_dwordx4 v[222:225], v247, s[98:99]
	s_waitcnt vmcnt(15)
	v_pk_fma_f32 v[76:77], v[140:141], v[76:77], v[226:227]
	v_pk_fma_f32 v[78:79], v[142:143], v[78:79], v[228:229]
	global_load_dwordx4 v[226:229], v249, s[98:99]
	s_waitcnt vmcnt(15)
	v_pk_fma_f32 v[72:73], v[148:149], v[72:73], v[230:231]
	v_pk_fma_f32 v[74:75], v[150:151], v[74:75], v[232:233]
	global_load_dwordx4 v[230:233], v251, s[98:99]
	s_waitcnt vmcnt(15)
	v_pk_fma_f32 v[68:69], v[152:153], v[68:69], v[234:235]
	v_pk_fma_f32 v[70:71], v[154:155], v[70:71], v[236:237]
	global_load_dwordx4 v[234:237], v253, s[98:99]
	s_waitcnt vmcnt(15)
	v_pk_fma_f32 v[64:65], v[132:133], v[64:65], v[162:163]
	v_pk_fma_f32 v[66:67], v[134:135], v[66:67], v[164:165]
	s_waitcnt vmcnt(14)
	v_pk_fma_f32 v[60:61], v[140:141], v[60:61], v[166:167]
	v_pk_fma_f32 v[62:63], v[142:143], v[62:63], v[168:169]
	s_waitcnt vmcnt(13)
	v_pk_fma_f32 v[56:57], v[148:149], v[56:57], v[170:171]
	v_pk_fma_f32 v[58:59], v[150:151], v[58:59], v[172:173]
	s_waitcnt vmcnt(12)
	v_pk_fma_f32 v[52:53], v[152:153], v[52:53], v[174:175]
	v_pk_fma_f32 v[54:55], v[154:155], v[54:55], v[176:177]
	s_waitcnt vmcnt(11)
	v_pk_fma_f32 v[48:49], v[132:133], v[48:49], v[178:179]
	v_pk_fma_f32 v[50:51], v[134:135], v[50:51], v[180:181]
	s_waitcnt vmcnt(10)
	v_pk_fma_f32 v[44:45], v[140:141], v[44:45], v[182:183]
	v_pk_fma_f32 v[46:47], v[142:143], v[46:47], v[184:185]
	s_waitcnt vmcnt(9)
	v_pk_fma_f32 v[40:41], v[148:149], v[40:41], v[186:187]
	v_pk_fma_f32 v[42:43], v[150:151], v[42:43], v[188:189]
	s_waitcnt vmcnt(8)
	v_pk_fma_f32 v[36:37], v[152:153], v[36:37], v[190:191]
	v_pk_fma_f32 v[38:39], v[154:155], v[38:39], v[192:193]
	s_waitcnt vmcnt(7)
	v_pk_fma_f32 v[32:33], v[132:133], v[32:33], v[194:195]
	v_pk_fma_f32 v[34:35], v[134:135], v[34:35], v[196:197]
	s_waitcnt vmcnt(6)
	v_pk_fma_f32 v[28:29], v[140:141], v[28:29], v[198:199]
	v_pk_fma_f32 v[30:31], v[142:143], v[30:31], v[200:201]
	s_waitcnt vmcnt(5)
	v_pk_fma_f32 v[24:25], v[148:149], v[24:25], v[214:215]
	v_pk_fma_f32 v[26:27], v[150:151], v[26:27], v[216:217]
	s_waitcnt vmcnt(4)
	v_pk_fma_f32 v[20:21], v[152:153], v[20:21], v[218:219]
	v_pk_fma_f32 v[22:23], v[154:155], v[22:23], v[220:221]
	s_waitcnt vmcnt(3)
	v_pk_fma_f32 v[16:17], v[132:133], v[16:17], v[222:223]
	v_pk_fma_f32 v[18:19], v[134:135], v[18:19], v[224:225]
	s_waitcnt vmcnt(2)
	v_pk_fma_f32 v[12:13], v[140:141], v[12:13], v[226:227]
	v_pk_fma_f32 v[14:15], v[142:143], v[14:15], v[228:229]
	s_waitcnt vmcnt(1)
	v_pk_fma_f32 v[8:9], v[148:149], v[8:9], v[230:231]
	v_pk_fma_f32 v[10:11], v[150:151], v[10:11], v[232:233]
	s_waitcnt vmcnt(0)
	v_pk_fma_f32 v[4:5], v[152:153], v[4:5], v[234:235]
	v_pk_fma_f32 v[6:7], v[154:155], v[6:7], v[236:237]
	s_waitcnt vmcnt(0)
	s_barrier
	v_mov_b32_e32 v247, v157
	v_add_u32_e32 v249, 0x40, v157
	v_add_u32_e32 v251, 0x200, v157
	v_add_u32_e32 v253, 0x240, v157
	global_store_dwordx4 v247, v[100:103], s[100:101]
	global_store_dwordx4 v249, v[108:111], s[100:101]
	global_store_dwordx4 v251, v[116:119], s[100:101]
	global_store_dwordx4 v253, v[124:127], s[100:101]
	s_add_u32 s100, s100, 0x10000
	s_addc_u32 s101, s101, 0
	global_store_dwordx4 v247, v[120:123], s[100:101]
	global_store_dwordx4 v249, v[128:131], s[100:101]
	global_store_dwordx4 v251, v[112:115], s[100:101]
	global_store_dwordx4 v253, v[104:107], s[100:101]
	s_add_u32 s100, s100, 0x10000
	s_addc_u32 s101, s101, 0
	global_store_dwordx4 v247, v[96:99], s[100:101]
	global_store_dwordx4 v249, v[92:95], s[100:101]
	global_store_dwordx4 v251, v[88:91], s[100:101]
	global_store_dwordx4 v253, v[84:87], s[100:101]
	s_add_u32 s100, s100, 0x10000
	s_addc_u32 s101, s101, 0
	global_store_dwordx4 v247, v[80:83], s[100:101]
	global_store_dwordx4 v249, v[76:79], s[100:101]
	global_store_dwordx4 v251, v[72:75], s[100:101]
	global_store_dwordx4 v253, v[68:71], s[100:101]
	s_add_u32 s100, s100, 0x50000
	s_addc_u32 s101, s101, 0
	global_store_dwordx4 v247, v[64:67], s[100:101]
	global_store_dwordx4 v249, v[60:63], s[100:101]
	global_store_dwordx4 v251, v[56:59], s[100:101]
	global_store_dwordx4 v253, v[52:55], s[100:101]
	s_add_u32 s100, s100, 0x10000
	s_addc_u32 s101, s101, 0
	global_store_dwordx4 v247, v[48:51], s[100:101]
	global_store_dwordx4 v249, v[44:47], s[100:101]
	global_store_dwordx4 v251, v[40:43], s[100:101]
	global_store_dwordx4 v253, v[36:39], s[100:101]
	s_add_u32 s100, s100, 0x10000
	s_addc_u32 s101, s101, 0
	global_store_dwordx4 v247, v[32:35], s[100:101]
	global_store_dwordx4 v249, v[28:31], s[100:101]
	global_store_dwordx4 v251, v[24:27], s[100:101]
	global_store_dwordx4 v253, v[20:23], s[100:101]
	s_add_u32 s100, s100, 0x10000
	s_addc_u32 s101, s101, 0
	global_store_dwordx4 v247, v[16:19], s[100:101]
	global_store_dwordx4 v249, v[12:15], s[100:101]
	global_store_dwordx4 v251, v[8:11], s[100:101]
	global_store_dwordx4 v253, v[4:7], s[100:101]

; __device__ __forceinline__ unsigned pk2(float lo, float hi) { unsigned r; asm("v_cvt_pk_bf16_f32 %0, %1, %2" : "=v"(r) : "v"(lo), "v"(hi)); return r; }
;     __device__ __forceinline__ void fused(f32x4 (&acc)[2][2][4][2], const Unit& u, int wr, int wc, int fr, int fq, LAS unsigned char* lds, int wid, int lane) const {
;     ...
;         if (h) {
;             stats(acc, u, wr, wc, fr, fq, lds, wid, lane, e2);
; #pragma unroll
;             for (int ai = 0; ai < 2; ++ai)
; #pragma unroll
;                 for (int m = 0; m < 4; ++m) { const int r = ai * HALF + wr * 64 + m * 16 + fr; const float rs = S[r]; bf16_t* hp = h + (size_t)(u.pm * BM + r) * D + col0;
; #pragma unroll
;                     for (int bj = 0; bj < 2; ++bj)
; #pragma unroll
;                         for (int n = 0; n < 2; ++n) { const f32x4 gv = *(const f32x4*)(g2 + col0 + bj * HALF + n * 16); const f32x4 o = acc[ai][bj][m][n] * rs * gv;
;                             u32x2 w; w.x = pk2(o[0], o[1]); w.y = pk2(o[2], o[3]); *(u32x2*)(hp + bj * HALF + n * 16) = w; }
;                     asm volatile("" ::: "memory"); }
.LBB0_590:
	s_or_b64 exec, exec, s[8:9]
	s_add_i32 s4, s20, 0x400
	s_ashr_i32 s5, s4, 31
	s_lshl_b64 s[4:5], s[4:5], 2
	s_add_u32 s0, s0, s4
	s_addc_u32 s2, s2, s5
	s_and_b64 s[4:5], exec, s[24:25]
	s_cselect_b32 s2, 0, s2
	s_cselect_b32 s0, 0, s0
	v_mov_b32_e32 v132, s0
	v_mov_b32_e32 v133, s2
	s_waitcnt lgkmcnt(0)
	s_barrier
	s_mov_b32 s16, s0
	s_mov_b32 s17, s2
	v_lshlrev_b32_e32 v156, 2, v0
	v_lshlrev_b32_e32 v162, 1, v0
	v_lshl_add_u32 v162, v145, 11, v162
	s_lshl_b32 s100, s35, 19
	s_add_u32 s98, s10, s100
	s_addc_u32 s99, s11, 0
	global_load_dwordx4 v[132:135], v156, s[16:17] offset:0
	global_load_dwordx4 v[140:143], v156, s[16:17] offset:64
	global_load_dwordx4 v[148:151], v156, s[16:17] offset:512
	global_load_dwordx4 v[152:155], v156, s[16:17] offset:576
	ds_read_b32 v246, v3 offset:4096
	ds_read_b32 v248, v3 offset:4160
	ds_read_b32 v250, v3 offset:4224
	ds_read_b32 v252, v3 offset:4288
	s_waitcnt lgkmcnt(3)
	v_pk_mul_f32 v[100:101], v[100:101], v[246:247] op_sel_hi:[1,0]
	v_pk_mul_f32 v[102:103], v[102:103], v[246:247] op_sel_hi:[1,0]
	s_waitcnt vmcnt(0)
	v_pk_mul_f32 v[100:101], v[132:133], v[100:101]
	v_pk_mul_f32 v[102:103], v[134:135], v[102:103]
	v_cvt_pk_bf16_f32 v100, v100, v101
	v_cvt_pk_bf16_f32 v101, v102, v103
	global_store_dwordx2 v162, v[100:101], s[98:99] offset:0
	v_pk_mul_f32 v[108:109], v[108:109], v[246:247] op_sel_hi:[1,0]
	v_pk_mul_f32 v[110:111], v[110:111], v[246:247] op_sel_hi:[1,0]
	v_pk_mul_f32 v[108:109], v[140:141], v[108:109]
	v_pk_mul_f32 v[110:111], v[142:143], v[110:111]
	v_cvt_pk_bf16_f32 v108, v108, v109
	v_cvt_pk_bf16_f32 v109, v110, v111
	global_store_dwordx2 v162, v[108:109], s[98:99] offset:32
	v_pk_mul_f32 v[116:117], v[116:117], v[246:247] op_sel_hi:[1,0]
	v_pk_mul_f32 v[118:119], v[118:119], v[246:247] op_sel_hi:[1,0]
	v_pk_mul_f32 v[116:117], v[148:149], v[116:117]
	v_pk_mul_f32 v[118:119], v[150:151], v[118:119]
	v_cvt_pk_bf16_f32 v116, v116, v117
	v_cvt_pk_bf16_f32 v117, v118, v119
	global_store_dwordx2 v162, v[116:117], s[98:99] offset:256
	v_pk_mul_f32 v[124:125], v[124:125], v[246:247] op_sel_hi:[1,0]
	v_pk_mul_f32 v[126:127], v[126:127], v[246:247] op_sel_hi:[1,0]
	v_pk_mul_f32 v[124:125], v[152:153], v[124:125]
	v_pk_mul_f32 v[126:127], v[154:155], v[126:127]
	v_cvt_pk_bf16_f32 v124, v124, v125
	v_cvt_pk_bf16_f32 v125, v126, v127
	global_store_dwordx2 v162, v[124:125], s[98:99] offset:288
	s_waitcnt lgkmcnt(2)
	s_add_u32 s98, s98, 0x8000
	s_addc_u32 s99, s99, 0
	v_pk_mul_f32 v[120:121], v[120:121], v[248:249] op_sel_hi:[1,0]
	v_pk_mul_f32 v[122:123], v[122:123], v[248:249] op_sel_hi:[1,0]
	v_pk_mul_f32 v[120:121], v[132:133], v[120:121]
	v_pk_mul_f32 v[122:123], v[134:135], v[122:123]
	v_cvt_pk_bf16_f32 v120, v120, v121
	v_cvt_pk_bf16_f32 v121, v122, v123
	global_store_dwordx2 v162, v[120:121], s[98:99] offset:0
	v_pk_mul_f32 v[128:129], v[128:129], v[248:249] op_sel_hi:[1,0]
	v_pk_mul_f32 v[130:131], v[130:131], v[248:249] op_sel_hi:[1,0]
	v_pk_mul_f32 v[128:129], v[140:141], v[128:129]
	v_pk_mul_f32 v[130:131], v[142:143], v[130:131]
	v_cvt_pk_bf16_f32 v128, v128, v129
	v_cvt_pk_bf16_f32 v129, v130, v131
	global_store_dwordx2 v162, v[128:129], s[98:99] offset:32
	v_pk_mul_f32 v[112:113], v[112:113], v[248:249] op_sel_hi:[1,0]
	v_pk_mul_f32 v[114:115], v[114:115], v[248:249] op_sel_hi:[1,0]
	v_pk_mul_f32 v[112:113], v[148:149], v[112:113]
	v_pk_mul_f32 v[114:115], v[150:151], v[114:115]
	v_cvt_pk_bf16_f32 v112, v112, v113
	v_cvt_pk_bf16_f32 v113, v114, v115
	global_store_dwordx2 v162, v[112:113], s[98:99] offset:256
	v_pk_mul_f32 v[104:105], v[104:105], v[248:249] op_sel_hi:[1,0]
	v_pk_mul_f32 v[106:107], v[106:107], v[248:249] op_sel_hi:[1,0]
	v_pk_mul_f32 v[104:105], v[152:153], v[104:105]
	v_pk_mul_f32 v[106:107], v[154:155], v[106:107]
	v_cvt_pk_bf16_f32 v104, v104, v105
	v_cvt_pk_bf16_f32 v105, v106, v107
	global_store_dwordx2 v162, v[104:105], s[98:99] offset:288
	s_waitcnt lgkmcnt(1)
	s_add_u32 s98, s98, 0x8000
	s_addc_u32 s99, s99, 0
	v_pk_mul_f32 v[96:97], v[96:97], v[250:251] op_sel_hi:[1,0]
	v_pk_mul_f32 v[98:99], v[98:99], v[250:251] op_sel_hi:[1,0]
	v_pk_mul_f32 v[96:97], v[132:133], v[96:97]
	v_pk_mul_f32 v[98:99], v[134:135], v[98:99]
	v_cvt_pk_bf16_f32 v96, v96, v97
	v_cvt_pk_bf16_f32 v97, v98, v99
	global_store_dwordx2 v162, v[96:97], s[98:99] offset:0
	v_pk_mul_f32 v[92:93], v[92:93], v[250:251] op_sel_hi:[1,0]
	v_pk_mul_f32 v[94:95], v[94:95], v[250:251] op_sel_hi:[1,0]
	v_pk_mul_f32 v[92:93], v[140:141], v[92:93]
	v_pk_mul_f32 v[94:95], v[142:143], v[94:95]
	v_cvt_pk_bf16_f32 v92, v92, v93
	v_cvt_pk_bf16_f32 v93, v94, v95
	global_store_dwordx2 v162, v[92:93], s[98:99] offset:32
	v_pk_mul_f32 v[88:89], v[88:89], v[250:251] op_sel_hi:[1,0]
	v_pk_mul_f32 v[90:91], v[90:91], v[250:251] op_sel_hi:[1,0]
	v_pk_mul_f32 v[88:89], v[148:149], v[88:89]
	v_pk_mul_f32 v[90:91], v[150:151], v[90:91]
	v_cvt_pk_bf16_f32 v88, v88, v89
	v_cvt_pk_bf16_f32 v89, v90, v91
	global_store_dwordx2 v162, v[88:89], s[98:99] offset:256
	v_pk_mul_f32 v[84:85], v[84:85], v[250:251] op_sel_hi:[1,0]
	v_pk_mul_f32 v[86:87], v[86:87], v[250:251] op_sel_hi:[1,0]
	v_pk_mul_f32 v[84:85], v[152:153], v[84:85]
	v_pk_mul_f32 v[86:87], v[154:155], v[86:87]
	v_cvt_pk_bf16_f32 v84, v84, v85
	v_cvt_pk_bf16_f32 v85, v86, v87
	global_store_dwordx2 v162, v[84:85], s[98:99] offset:288
	s_waitcnt lgkmcnt(0)
; __device__ __forceinline__ unsigned pk2(float lo, float hi) { unsigned r; asm("v_cvt_pk_bf16_f32 %0, %1, %2" : "=v"(r) : "v"(lo), "v"(hi)); return r; }
;     __device__ __forceinline__ void fused(f32x4 (&acc)[2][2][4][2], const Unit& u, int wr, int wc, int fr, int fq, LAS unsigned char* lds, int wid, int lane) const {
;     ...
; #pragma unroll
;             for (int ai = 0; ai < 2; ++ai)
; #pragma unroll
;                 for (int m = 0; m < 4; ++m) { const int r = ai * HALF + wr * 64 + m * 16 + fr; const float rs = S[r]; bf16_t* hp = h + (size_t)(u.pm * BM + r) * D + col0;
; #pragma unroll
;                     for (int bj = 0; bj < 2; ++bj)
; #pragma unroll
;                         for (int n = 0; n < 2; ++n) { const f32x4 gv = *(const f32x4*)(g2 + col0 + bj * HALF + n * 16); const f32x4 o = acc[ai][bj][m][n] * rs * gv;
;                             u32x2 w; w.x = pk2(o[0], o[1]); w.y = pk2(o[2], o[3]); *(u32x2*)(hp + bj * HALF + n * 16) = w; }
;                     asm volatile("" ::: "memory"); }
	s_add_u32 s98, s98, 0x8000
	s_addc_u32 s99, s99, 0
	v_pk_mul_f32 v[80:81], v[80:81], v[252:253] op_sel_hi:[1,0]
	v_pk_mul_f32 v[82:83], v[82:83], v[252:253] op_sel_hi:[1,0]
	v_pk_mul_f32 v[80:81], v[132:133], v[80:81]
	v_pk_mul_f32 v[82:83], v[134:135], v[82:83]
	v_cvt_pk_bf16_f32 v80, v80, v81
	v_cvt_pk_bf16_f32 v81, v82, v83
	global_store_dwordx2 v162, v[80:81], s[98:99] offset:0
	v_pk_mul_f32 v[76:77], v[76:77], v[252:253] op_sel_hi:[1,0]
	v_pk_mul_f32 v[78:79], v[78:79], v[252:253] op_sel_hi:[1,0]
	v_pk_mul_f32 v[76:77], v[140:141], v[76:77]
	v_pk_mul_f32 v[78:79], v[142:143], v[78:79]
	v_cvt_pk_bf16_f32 v76, v76, v77
	v_cvt_pk_bf16_f32 v77, v78, v79
	global_store_dwordx2 v162, v[76:77], s[98:99] offset:32
	v_pk_mul_f32 v[72:73], v[72:73], v[252:253] op_sel_hi:[1,0]
	v_pk_mul_f32 v[74:75], v[74:75], v[252:253] op_sel_hi:[1,0]
	v_pk_mul_f32 v[72:73], v[148:149], v[72:73]
	v_pk_mul_f32 v[74:75], v[150:151], v[74:75]
	v_cvt_pk_bf16_f32 v72, v72, v73
	v_cvt_pk_bf16_f32 v73, v74, v75
	global_store_dwordx2 v162, v[72:73], s[98:99] offset:256
	v_pk_mul_f32 v[68:69], v[68:69], v[252:253] op_sel_hi:[1,0]
	v_pk_mul_f32 v[70:71], v[70:71], v[252:253] op_sel_hi:[1,0]
	v_pk_mul_f32 v[68:69], v[152:153], v[68:69]
	v_pk_mul_f32 v[70:71], v[154:155], v[70:71]
	v_cvt_pk_bf16_f32 v68, v68, v69
	v_cvt_pk_bf16_f32 v69, v70, v71
	global_store_dwordx2 v162, v[68:69], s[98:99] offset:288
	ds_read_b32 v246, v3 offset:4608
	ds_read_b32 v248, v3 offset:4672
	ds_read_b32 v250, v3 offset:4736
	ds_read_b32 v252, v3 offset:4800
	s_waitcnt lgkmcnt(3)
	s_add_u32 s98, s98, 0x28000
	s_addc_u32 s99, s99, 0
	v_pk_mul_f32 v[64:65], v[64:65], v[246:247] op_sel_hi:[1,0]
	v_pk_mul_f32 v[66:67], v[66:67], v[246:247] op_sel_hi:[1,0]
	v_pk_mul_f32 v[64:65], v[132:133], v[64:65]
	v_pk_mul_f32 v[66:67], v[134:135], v[66:67]
	v_cvt_pk_bf16_f32 v64, v64, v65
	v_cvt_pk_bf16_f32 v65, v66, v67
	global_store_dwordx2 v162, v[64:65], s[98:99] offset:0
	v_pk_mul_f32 v[60:61], v[60:61], v[246:247] op_sel_hi:[1,0]
	v_pk_mul_f32 v[62:63], v[62:63], v[246:247] op_sel_hi:[1,0]
	v_pk_mul_f32 v[60:61], v[140:141], v[60:61]
	v_pk_mul_f32 v[62:63], v[142:143], v[62:63]
	v_cvt_pk_bf16_f32 v60, v60, v61
	v_cvt_pk_bf16_f32 v61, v62, v63
	global_store_dwordx2 v162, v[60:61], s[98:99] offset:32
	v_pk_mul_f32 v[56:57], v[56:57], v[246:247] op_sel_hi:[1,0]
	v_pk_mul_f32 v[58:59], v[58:59], v[246:247] op_sel_hi:[1,0]
	v_pk_mul_f32 v[56:57], v[148:149], v[56:57]
	v_pk_mul_f32 v[58:59], v[150:151], v[58:59]
	v_cvt_pk_bf16_f32 v56, v56, v57
	v_cvt_pk_bf16_f32 v57, v58, v59
	global_store_dwordx2 v162, v[56:57], s[98:99] offset:256
	v_pk_mul_f32 v[52:53], v[52:53], v[246:247] op_sel_hi:[1,0]
	v_pk_mul_f32 v[54:55], v[54:55], v[246:247] op_sel_hi:[1,0]
	v_pk_mul_f32 v[52:53], v[152:153], v[52:53]
	v_pk_mul_f32 v[54:55], v[154:155], v[54:55]
	v_cvt_pk_bf16_f32 v52, v52, v53
	v_cvt_pk_bf16_f32 v53, v54, v55
	global_store_dwordx2 v162, v[52:53], s[98:99] offset:288
	s_waitcnt lgkmcnt(2)
; __device__ __forceinline__ unsigned pk2(float lo, float hi) { unsigned r; asm("v_cvt_pk_bf16_f32 %0, %1, %2" : "=v"(r) : "v"(lo), "v"(hi)); return r; }
;     __device__ __forceinline__ void fused(f32x4 (&acc)[2][2][4][2], const Unit& u, int wr, int wc, int fr, int fq, LAS unsigned char* lds, int wid, int lane) const {
;     ...
; #pragma unroll
;             for (int ai = 0; ai < 2; ++ai)
; #pragma unroll
;                 for (int m = 0; m < 4; ++m) { const int r = ai * HALF + wr * 64 + m * 16 + fr; const float rs = S[r]; bf16_t* hp = h + (size_t)(u.pm * BM + r) * D + col0;
; #pragma unroll
;                     for (int bj = 0; bj < 2; ++bj)
; #pragma unroll
;                         for (int n = 0; n < 2; ++n) { const f32x4 gv = *(const f32x4*)(g2 + col0 + bj * HALF + n * 16); const f32x4 o = acc[ai][bj][m][n] * rs * gv;
;                             u32x2 w; w.x = pk2(o[0], o[1]); w.y = pk2(o[2], o[3]); *(u32x2*)(hp + bj * HALF + n * 16) = w; }
;                     asm volatile("" ::: "memory"); }
	s_add_u32 s98, s98, 0x8000
	s_addc_u32 s99, s99, 0
	v_pk_mul_f32 v[48:49], v[48:49], v[248:249] op_sel_hi:[1,0]
	v_pk_mul_f32 v[50:51], v[50:51], v[248:249] op_sel_hi:[1,0]
	v_pk_mul_f32 v[48:49], v[132:133], v[48:49]
	v_pk_mul_f32 v[50:51], v[134:135], v[50:51]
	v_cvt_pk_bf16_f32 v48, v48, v49
	v_cvt_pk_bf16_f32 v49, v50, v51
	global_store_dwordx2 v162, v[48:49], s[98:99] offset:0
	v_pk_mul_f32 v[44:45], v[44:45], v[248:249] op_sel_hi:[1,0]
	v_pk_mul_f32 v[46:47], v[46:47], v[248:249] op_sel_hi:[1,0]
	v_pk_mul_f32 v[44:45], v[140:141], v[44:45]
	v_pk_mul_f32 v[46:47], v[142:143], v[46:47]
	v_cvt_pk_bf16_f32 v44, v44, v45
	v_cvt_pk_bf16_f32 v45, v46, v47
	global_store_dwordx2 v162, v[44:45], s[98:99] offset:32
	v_pk_mul_f32 v[40:41], v[40:41], v[248:249] op_sel_hi:[1,0]
	v_pk_mul_f32 v[42:43], v[42:43], v[248:249] op_sel_hi:[1,0]
	v_pk_mul_f32 v[40:41], v[148:149], v[40:41]
	v_pk_mul_f32 v[42:43], v[150:151], v[42:43]
	v_cvt_pk_bf16_f32 v40, v40, v41
	v_cvt_pk_bf16_f32 v41, v42, v43
	global_store_dwordx2 v162, v[40:41], s[98:99] offset:256
	v_pk_mul_f32 v[36:37], v[36:37], v[248:249] op_sel_hi:[1,0]
	v_pk_mul_f32 v[38:39], v[38:39], v[248:249] op_sel_hi:[1,0]
	v_pk_mul_f32 v[36:37], v[152:153], v[36:37]
	v_pk_mul_f32 v[38:39], v[154:155], v[38:39]
	v_cvt_pk_bf16_f32 v36, v36, v37
	v_cvt_pk_bf16_f32 v37, v38, v39
	global_store_dwordx2 v162, v[36:37], s[98:99] offset:288
	s_waitcnt lgkmcnt(1)
	s_add_u32 s98, s98, 0x8000
	s_addc_u32 s99, s99, 0
	v_pk_mul_f32 v[32:33], v[32:33], v[250:251] op_sel_hi:[1,0]
	v_pk_mul_f32 v[34:35], v[34:35], v[250:251] op_sel_hi:[1,0]
	v_pk_mul_f32 v[32:33], v[132:133], v[32:33]
	v_pk_mul_f32 v[34:35], v[134:135], v[34:35]
	v_cvt_pk_bf16_f32 v32, v32, v33
	v_cvt_pk_bf16_f32 v33, v34, v35
	global_store_dwordx2 v162, v[32:33], s[98:99] offset:0
	v_pk_mul_f32 v[28:29], v[28:29], v[250:251] op_sel_hi:[1,0]
	v_pk_mul_f32 v[30:31], v[30:31], v[250:251] op_sel_hi:[1,0]
	v_pk_mul_f32 v[28:29], v[140:141], v[28:29]
	v_pk_mul_f32 v[30:31], v[142:143], v[30:31]
	v_cvt_pk_bf16_f32 v28, v28, v29
	v_cvt_pk_bf16_f32 v29, v30, v31
	global_store_dwordx2 v162, v[28:29], s[98:99] offset:32
	v_pk_mul_f32 v[24:25], v[24:25], v[250:251] op_sel_hi:[1,0]
	v_pk_mul_f32 v[26:27], v[26:27], v[250:251] op_sel_hi:[1,0]
	v_pk_mul_f32 v[24:25], v[148:149], v[24:25]
	v_pk_mul_f32 v[26:27], v[150:151], v[26:27]
	v_cvt_pk_bf16_f32 v24, v24, v25
	v_cvt_pk_bf16_f32 v25, v26, v27
	global_store_dwordx2 v162, v[24:25], s[98:99] offset:256
	v_pk_mul_f32 v[20:21], v[20:21], v[250:251] op_sel_hi:[1,0]
	v_pk_mul_f32 v[22:23], v[22:23], v[250:251] op_sel_hi:[1,0]
	v_pk_mul_f32 v[20:21], v[152:153], v[20:21]
	v_pk_mul_f32 v[22:23], v[154:155], v[22:23]
	v_cvt_pk_bf16_f32 v20, v20, v21
	v_cvt_pk_bf16_f32 v21, v22, v23
	global_store_dwordx2 v162, v[20:21], s[98:99] offset:288
	s_waitcnt lgkmcnt(0)
	s_add_u32 s98, s98, 0x8000
	s_addc_u32 s99, s99, 0
	v_pk_mul_f32 v[16:17], v[16:17], v[252:253] op_sel_hi:[1,0]
	v_pk_mul_f32 v[18:19], v[18:19], v[252:253] op_sel_hi:[1,0]
	v_pk_mul_f32 v[16:17], v[132:133], v[16:17]
	v_pk_mul_f32 v[18:19], v[134:135], v[18:19]
	v_cvt_pk_bf16_f32 v16, v16, v17
	v_cvt_pk_bf16_f32 v17, v18, v19
	global_store_dwordx2 v162, v[16:17], s[98:99] offset:0
	v_pk_mul_f32 v[12:13], v[12:13], v[252:253] op_sel_hi:[1,0]
	v_pk_mul_f32 v[14:15], v[14:15], v[252:253] op_sel_hi:[1,0]
	v_pk_mul_f32 v[12:13], v[140:141], v[12:13]
	v_pk_mul_f32 v[14:15], v[142:143], v[14:15]
	v_cvt_pk_bf16_f32 v12, v12, v13
	v_cvt_pk_bf16_f32 v13, v14, v15
	global_store_dwordx2 v162, v[12:13], s[98:99] offset:32
	v_pk_mul_f32 v[8:9], v[8:9], v[252:253] op_sel_hi:[1,0]
	v_pk_mul_f32 v[10:11], v[10:11], v[252:253] op_sel_hi:[1,0]
	v_pk_mul_f32 v[8:9], v[148:149], v[8:9]
	v_pk_mul_f32 v[10:11], v[150:151], v[10:11]
	v_cvt_pk_bf16_f32 v8, v8, v9
	v_cvt_pk_bf16_f32 v9, v10, v11
	global_store_dwordx2 v162, v[8:9], s[98:99] offset:256
	v_pk_mul_f32 v[4:5], v[4:5], v[252:253] op_sel_hi:[1,0]
	v_pk_mul_f32 v[6:7], v[6:7], v[252:253] op_sel_hi:[1,0]
	v_pk_mul_f32 v[4:5], v[152:153], v[4:5]
	v_pk_mul_f32 v[6:7], v[154:155], v[6:7]
	v_cvt_pk_bf16_f32 v4, v4, v5
	v_cvt_pk_bf16_f32 v5, v6, v7
	global_store_dwordx2 v162, v[4:5], s[98:99] offset:288

; __global__ void __launch_bounds__(512, 2) mega(Params p) {
	.amdhsa_kernel _Z4mega6Params
		.amdhsa_group_segment_fixed_size 0
		.amdhsa_private_segment_fixed_size 0
		.amdhsa_kernarg_size 624
		.amdhsa_user_sgpr_count 2
		.amdhsa_user_sgpr_dispatch_ptr 0
		.amdhsa_user_sgpr_queue_ptr 0
		.amdhsa_user_sgpr_kernarg_segment_ptr 1
		.amdhsa_user_sgpr_dispatch_id 0
		.amdhsa_user_sgpr_kernarg_preload_length 0
		.amdhsa_user_sgpr_kernarg_preload_offset 0
		.amdhsa_user_sgpr_private_segment_size 0
		.amdhsa_uses_dynamic_stack 0
		.amdhsa_enable_private_segment 0
		.amdhsa_system_sgpr_workgroup_id_x 1
		.amdhsa_system_sgpr_workgroup_id_y 0
		.amdhsa_system_sgpr_workgroup_id_z 0
		.amdhsa_system_sgpr_workgroup_info 0
		.amdhsa_system_vgpr_workitem_id 2
		.amdhsa_next_free_vgpr 256
		.amdhsa_next_free_sgpr 102
		.amdhsa_accum_offset 256
		.amdhsa_reserve_vcc 1
		.amdhsa_float_round_mode_32 0
		.amdhsa_float_round_mode_16_64 0
		.amdhsa_float_denorm_mode_32 3
		.amdhsa_float_denorm_mode_16_64 3
		.amdhsa_dx10_clamp 1
		.amdhsa_ieee_mode 1
		.amdhsa_fp16_overflow 0
		.amdhsa_tg_split 0
		.amdhsa_exception_fp_ieee_invalid_op 0
		.amdhsa_exception_fp_denorm_src 0
		.amdhsa_exception_fp_ieee_div_zero 0
		.amdhsa_exception_fp_ieee_overflow 0
		.amdhsa_exception_fp_ieee_underflow 0
		.amdhsa_exception_fp_ieee_inexact 0
		.amdhsa_exception_int_div_zero 0
	.end_amdhsa_kernel

; __global__ void __launch_bounds__(512, 2) mega(Params p) {
amdhsa.kernels:
  - .agpr_count:     0
    .args:
      - .offset:         0
        .size:           368
        .value_kind:     by_value
      - .offset:         368
        .size:           4
        .value_kind:     hidden_block_count_x
      - .offset:         372
        .size:           4
        .value_kind:     hidden_block_count_y
      - .offset:         376
        .size:           4
        .value_kind:     hidden_block_count_z
      - .offset:         380
        .size:           2
        .value_kind:     hidden_group_size_x
      - .offset:         382
        .size:           2
        .value_kind:     hidden_group_size_y
      - .offset:         384
        .size:           2
        .value_kind:     hidden_group_size_z
      - .offset:         386
        .size:           2
        .value_kind:     hidden_remainder_x
      - .offset:         388
        .size:           2
        .value_kind:     hidden_remainder_y
      - .offset:         390
        .size:           2
        .value_kind:     hidden_remainder_z
      - .offset:         408
        .size:           8
        .value_kind:     hidden_global_offset_x
      - .offset:         416
        .size:           8
        .value_kind:     hidden_global_offset_y
      - .offset:         424
        .size:           8
        .value_kind:     hidden_global_offset_z
      - .offset:         432
        .size:           2
        .value_kind:     hidden_grid_dims
      - .offset:         456
        .size:           8
        .value_kind:     hidden_multigrid_sync_arg
      - .offset:         488
        .size:           4
        .value_kind:     hidden_dynamic_lds_size
    .group_segment_fixed_size: 0
    .kernarg_segment_align: 8
    .kernarg_segment_size: 624
    .language:       OpenCL C
    .language_version:
      - 2
      - 0
    .max_flat_workgroup_size: 512
    .name:           _Z4mega6Params
    .private_segment_fixed_size: 0
    .sgpr_count:     108
    .sgpr_spill_count: 61
    .symbol:         _Z4mega6Params.kd
    .uniform_work_group_size: 1
    .uses_dynamic_stack: false
    .vgpr_count:     256
    .vgpr_spill_count: 0
    .wavefront_size: 64
